# adds two more brief priority-0 windows per 32-MFMA segment in the six GEMM K-loops (after MFMA 8 and 24, like the one between the two MMA macros)
# speedup vs baseline: 1.0242x; 1.0015x over previous
; #define PG8_STAGE(bufoff, gbase, voff) do { _Pragma("unroll") for (int _i = 0; _i < 2; ++_i) \
;         __builtin_amdgcn_global_load_lds((const unsigned*)((const char*)(gbase) + (voff)[_i]), (PG8_LAS unsigned*)(lds + (bufoff) + ldsw + _i * 8192), 16, 0, 0); } while (0)
; #define PG8_LDA(dst, b, h) do { _Pragma("unroll") for (int m = 0; m < 4; ++m) _Pragma("unroll") for (int k = 0; k < 2; ++k) dst[m][k] = *(const PG8_LAS bf16x8*)(lds + PG8_SA(b, h) + aoff + m * 2048 + k * 1024); } while (0)
; #define PG8_LDB(dst, b, h) do { _Pragma("unroll") for (int n = 0; n < 2; ++n) _Pragma("unroll") for (int k = 0; k < 2; ++k) dst[n][k] = *(const PG8_LAS bf16x8*)(lds + PG8_SB(b, h) + boff + n * 2048 + k * 1024); } while (0)
; #define PG8_MMA(ai, bj, At, Bt) do { __builtin_amdgcn_s_setprio(1); _Pragma("unroll") for (int m = 0; m < 4; ++m) _Pragma("unroll") for (int n = 0; n < 2; ++n) _Pragma("unroll") for (int k = 0; k < 2; ++k) \
;         acc[ai][bj][m][n] = __builtin_amdgcn_mfma_f32_16x16x32_bf16(Bt[n][k], At[m][k], acc[ai][bj][m][n], 0, 0, 0); __builtin_amdgcn_s_setprio(0); } while (0)
; #define PG8_WAIT_V(n) asm volatile("s_waitcnt vmcnt(" #n ")" ::: "memory")
; #define PG8_WAIT_L(n) asm volatile("s_waitcnt lgkmcnt(" #n ")" ::: "memory")
; #define PG8_BAR __builtin_amdgcn_s_barrier()
; #define PG8_SCHED __builtin_amdgcn_sched_barrier(0)
; template <class Epi, class Sched, bool ALIGN_EPI = false, bool SP2 = false>
; __device__ __forceinline__ void gemm_phase(PG8_LAS unsigned char* lds, const Gemm g, const Sched& S, const Epi& E) {
;     ...
;             if constexpr (SP2) {
;             PG8_LDB(B0, 0, 0); PG8_LDB(B1, 0, 1); PG8_SCHED; PG8_LDA(At, 0, 0); PG8_STAGE(PG8_SA(1, 1), a1 + hstep, voffA);
;             PG8_WAIT_V(8); PG8_WAIT_L(0); PG8_BAR; PG8_MMA(0, 0, At, B0); PG8_MMA(0, 1, At, B1); PG8_BAR; PG8_SCHED;
;             PG8_LDA(At, 0, 1); PG8_STAGE(PG8_SB(0, 0), b2, voffB); PG8_STAGE(PG8_SB(0, 1), b2 + hstep, voffB); PG8_STAGE(PG8_SA(0, 0), a2, voffA);
;             PG8_WAIT_V(8); PG8_WAIT_L(0); PG8_BAR; PG8_MMA(1, 0, At, B0); PG8_MMA(1, 1, At, B1); PG8_BAR; PG8_SCHED;
.LBB0_36:
	s_add_u32 s18, s58, 0xffe00080
	s_addc_u32 s19, s59, -1
	s_add_i32 s47, 0, 0x10000
	s_cmpk_eq_i32 s46, 0x7c
	s_cselect_b32 s63, s45, s19
	s_cselect_b32 s62, s73, s18
	v_add_u32_e32 v160, s47, v143
	s_cselect_b32 s19, s37, s79
	s_cselect_b32 s18, s84, s78
	s_add_i32 s80, 0, 0x14000
	ds_read_b128 v[156:159], v160
	ds_read_b128 v[164:167], v160 offset:1024
	ds_read_b128 v[168:171], v160 offset:2048
	ds_read_b128 v[172:175], v160 offset:3072
	v_add_u32_e32 v160, s80, v143
	ds_read_b128 v[176:179], v160
	ds_read_b128 v[180:183], v160 offset:1024
	ds_read_b128 v[184:187], v160 offset:2048
	ds_read_b128 v[204:207], v160 offset:3072
	v_lshl_add_u64 v[160:161], s[58:59], 0, v[152:153]
	s_add_i32 m0, s5, 0xc000
	ds_read_b128 v[208:211], v163
	ds_read_b128 v[212:215], v163 offset:1024
	ds_read_b128 v[216:219], v163 offset:2048
	ds_read_b128 v[220:223], v163 offset:3072
	ds_read_b128 v[224:227], v163 offset:4096
	ds_read_b128 v[228:231], v163 offset:5120
	ds_read_b128 v[232:235], v163 offset:6144
	ds_read_b128 v[236:239], v163 offset:7168
	global_load_lds_dwordx4 v[160:161], off
	v_lshl_add_u64 v[160:161], s[58:59], 0, v[154:155]
	s_add_i32 m0, s5, 0xe000
	s_nop 0
	global_load_lds_dwordx4 v[160:161], off
	s_waitcnt vmcnt(8)
	s_waitcnt lgkmcnt(0)
	s_barrier
	s_setprio 1
	s_waitcnt lgkmcnt(0)
	v_mfma_f32_16x16x32_bf16 v[126:129], v[156:159], v[208:211], v[126:129]
	v_mfma_f32_16x16x32_bf16 v[122:125], v[168:171], v[208:211], v[122:125]
	v_mfma_f32_16x16x32_bf16 v[110:113], v[156:159], v[216:219], v[110:113]
	v_mfma_f32_16x16x32_bf16 v[106:109], v[168:171], v[216:219], v[106:109]
	v_mfma_f32_16x16x32_bf16 v[94:97], v[156:159], v[224:227], v[94:97]
	v_mfma_f32_16x16x32_bf16 v[90:93], v[168:171], v[224:227], v[90:93]
	v_mfma_f32_16x16x32_bf16 v[78:81], v[156:159], v[232:235], v[78:81]
	v_mfma_f32_16x16x32_bf16 v[74:77], v[168:171], v[232:235], v[74:77]
	s_setprio 0
	s_setprio 1
	v_mfma_f32_16x16x32_bf16 v[126:129], v[164:167], v[212:215], v[126:129]
	v_mfma_f32_16x16x32_bf16 v[122:125], v[172:175], v[212:215], v[122:125]
	v_mfma_f32_16x16x32_bf16 v[110:113], v[164:167], v[220:223], v[110:113]
	v_mfma_f32_16x16x32_bf16 v[106:109], v[172:175], v[220:223], v[106:109]
	v_mfma_f32_16x16x32_bf16 v[94:97], v[164:167], v[228:231], v[94:97]
	v_mfma_f32_16x16x32_bf16 v[90:93], v[172:175], v[228:231], v[90:93]
	v_mfma_f32_16x16x32_bf16 v[78:81], v[164:167], v[236:239], v[78:81]
	v_mfma_f32_16x16x32_bf16 v[74:77], v[172:175], v[236:239], v[74:77]
	s_setprio 0
	s_setprio 1
	v_mfma_f32_16x16x32_bf16 v[118:121], v[176:179], v[208:211], v[118:121]
	v_mfma_f32_16x16x32_bf16 v[114:117], v[184:187], v[208:211], v[114:117]
	v_mfma_f32_16x16x32_bf16 v[102:105], v[176:179], v[216:219], v[102:105]
	v_mfma_f32_16x16x32_bf16 v[98:101], v[184:187], v[216:219], v[98:101]
	v_mfma_f32_16x16x32_bf16 v[86:89], v[176:179], v[224:227], v[86:89]
	v_mfma_f32_16x16x32_bf16 v[82:85], v[184:187], v[224:227], v[82:85]
	v_mfma_f32_16x16x32_bf16 v[70:73], v[176:179], v[232:235], v[70:73]
	v_mfma_f32_16x16x32_bf16 v[66:69], v[184:187], v[232:235], v[66:69]
	s_setprio 0
	s_setprio 1
	v_mfma_f32_16x16x32_bf16 v[118:121], v[180:183], v[212:215], v[118:121]
	v_mfma_f32_16x16x32_bf16 v[114:117], v[204:207], v[212:215], v[114:117]
	v_mfma_f32_16x16x32_bf16 v[102:105], v[180:183], v[220:223], v[102:105]
	v_mfma_f32_16x16x32_bf16 v[98:101], v[204:207], v[220:223], v[98:101]
	v_mfma_f32_16x16x32_bf16 v[86:89], v[180:183], v[228:231], v[86:89]
	v_mfma_f32_16x16x32_bf16 v[82:85], v[204:207], v[228:231], v[82:85]
	v_mfma_f32_16x16x32_bf16 v[70:73], v[180:183], v[236:239], v[70:73]
	v_mfma_f32_16x16x32_bf16 v[66:69], v[204:207], v[236:239], v[66:69]
	s_setprio 0
	s_barrier
	s_add_i32 s47, s47, s4
	v_lshl_add_u64 v[160:161], s[18:19], 0, v[148:149]
	s_mov_b32 m0, s47
	ds_read_b128 v[208:211], v163 offset:16384
	ds_read_b128 v[212:215], v163 offset:17408
	ds_read_b128 v[216:219], v163 offset:18432
	ds_read_b128 v[220:223], v163 offset:19456
	ds_read_b128 v[224:227], v163 offset:20480
	ds_read_b128 v[228:231], v163 offset:21504
	ds_read_b128 v[232:235], v163 offset:22528
	ds_read_b128 v[236:239], v163 offset:23552
	global_load_lds_dwordx4 v[160:161], off
	s_add_i32 m0, s47, 0x2000
	s_add_u32 s76, s18, 0x200000
	v_lshl_add_u64 v[240:241], s[18:19], 0, v[144:145]
	s_addc_u32 s77, s19, 0
	s_add_i32 s47, s80, s4
	global_load_lds_dwordx4 v[240:241], off
	v_lshl_add_u64 v[242:243], s[76:77], 0, v[148:149]
	s_mov_b32 m0, s47
	v_lshl_add_u64 v[244:245], s[62:63], 0, v[146:147]
	global_load_lds_dwordx4 v[242:243], off
	v_lshl_add_u64 v[242:243], s[76:77], 0, v[144:145]
	s_add_i32 m0, s47, 0x2000
	s_nop 0
	global_load_lds_dwordx4 v[242:243], off
	v_lshl_add_u64 v[242:243], s[62:63], 0, v[150:151]
	s_mov_b32 m0, s5
	s_nop 0
	global_load_lds_dwordx4 v[242:243], off
	s_mov_b32 m0, s30
	s_nop 0
	global_load_lds_dwordx4 v[244:245], off
	s_waitcnt vmcnt(8)
	s_waitcnt lgkmcnt(0)
	s_barrier
; #define PG8_STAGE(bufoff, gbase, voff) do { _Pragma("unroll") for (int _i = 0; _i < 2; ++_i) \
;         __builtin_amdgcn_global_load_lds((const unsigned*)((const char*)(gbase) + (voff)[_i]), (PG8_LAS unsigned*)(lds + (bufoff) + ldsw + _i * 8192), 16, 0, 0); } while (0)
; #define PG8_LDA(dst, b, h) do { _Pragma("unroll") for (int m = 0; m < 4; ++m) _Pragma("unroll") for (int k = 0; k < 2; ++k) dst[m][k] = *(const PG8_LAS bf16x8*)(lds + PG8_SA(b, h) + aoff + m * 2048 + k * 1024); } while (0)
; #define PG8_LDB(dst, b, h) do { _Pragma("unroll") for (int n = 0; n < 2; ++n) _Pragma("unroll") for (int k = 0; k < 2; ++k) dst[n][k] = *(const PG8_LAS bf16x8*)(lds + PG8_SB(b, h) + boff + n * 2048 + k * 1024); } while (0)
; #define PG8_MMA(ai, bj, At, Bt) do { __builtin_amdgcn_s_setprio(1); _Pragma("unroll") for (int m = 0; m < 4; ++m) _Pragma("unroll") for (int n = 0; n < 2; ++n) _Pragma("unroll") for (int k = 0; k < 2; ++k) \
;         acc[ai][bj][m][n] = __builtin_amdgcn_mfma_f32_16x16x32_bf16(Bt[n][k], At[m][k], acc[ai][bj][m][n], 0, 0, 0); __builtin_amdgcn_s_setprio(0); } while (0)
; #define PG8_WAIT_V(n) asm volatile("s_waitcnt vmcnt(" #n ")" ::: "memory")
; #define PG8_WAIT_L(n) asm volatile("s_waitcnt lgkmcnt(" #n ")" ::: "memory")
; #define PG8_BAR __builtin_amdgcn_s_barrier()
; #define PG8_SCHED __builtin_amdgcn_sched_barrier(0)
; template <class Epi, class Sched, bool ALIGN_EPI = false, bool SP2 = false>
; __device__ __forceinline__ void gemm_phase(PG8_LAS unsigned char* lds, const Gemm g, const Sched& S, const Epi& E) {
;     ...
;             PG8_WAIT_V(8); PG8_WAIT_L(0); PG8_BAR; PG8_MMA(1, 0, At, B0); PG8_MMA(1, 1, At, B1); PG8_BAR; PG8_SCHED;
;             PG8_LDB(B0, 1, 0); PG8_LDB(B1, 1, 1); PG8_SCHED; PG8_LDA(At, 1, 0); PG8_STAGE(PG8_SA(0, 1), a2 + hstep, voffA);
;             PG8_WAIT_V(8); PG8_WAIT_L(0); PG8_BAR; PG8_MMA(0, 0, At, B0); PG8_MMA(0, 1, At, B1); PG8_BAR; PG8_SCHED;
	s_setprio 1
	s_waitcnt lgkmcnt(0)
	v_mfma_f32_16x16x32_bf16 v[62:65], v[156:159], v[208:211], v[62:65]
	v_mfma_f32_16x16x32_bf16 v[58:61], v[168:171], v[208:211], v[58:61]
	v_mfma_f32_16x16x32_bf16 v[46:49], v[156:159], v[216:219], v[46:49]
	v_mfma_f32_16x16x32_bf16 v[42:45], v[168:171], v[216:219], v[42:45]
	v_mfma_f32_16x16x32_bf16 v[30:33], v[156:159], v[224:227], v[30:33]
	v_mfma_f32_16x16x32_bf16 v[26:29], v[168:171], v[224:227], v[26:29]
	v_mfma_f32_16x16x32_bf16 v[14:17], v[156:159], v[232:235], v[14:17]
	v_mfma_f32_16x16x32_bf16 v[10:13], v[168:171], v[232:235], v[10:13]
	s_setprio 0
	s_setprio 1
	v_mfma_f32_16x16x32_bf16 v[62:65], v[164:167], v[212:215], v[62:65]
	v_mfma_f32_16x16x32_bf16 v[58:61], v[172:175], v[212:215], v[58:61]
	v_mfma_f32_16x16x32_bf16 v[46:49], v[164:167], v[220:223], v[46:49]
	v_mfma_f32_16x16x32_bf16 v[42:45], v[172:175], v[220:223], v[42:45]
	v_mfma_f32_16x16x32_bf16 v[30:33], v[164:167], v[228:231], v[30:33]
	v_mfma_f32_16x16x32_bf16 v[26:29], v[172:175], v[228:231], v[26:29]
	v_mfma_f32_16x16x32_bf16 v[14:17], v[164:167], v[236:239], v[14:17]
	v_mfma_f32_16x16x32_bf16 v[10:13], v[172:175], v[236:239], v[10:13]
	s_setprio 0
	s_setprio 1
	v_mfma_f32_16x16x32_bf16 v[54:57], v[176:179], v[208:211], v[54:57]
	v_mfma_f32_16x16x32_bf16 v[50:53], v[184:187], v[208:211], v[50:53]
	v_mfma_f32_16x16x32_bf16 v[38:41], v[176:179], v[216:219], v[38:41]
	v_mfma_f32_16x16x32_bf16 v[34:37], v[184:187], v[216:219], v[34:37]
	v_mfma_f32_16x16x32_bf16 v[22:25], v[176:179], v[224:227], v[22:25]
	v_mfma_f32_16x16x32_bf16 v[18:21], v[184:187], v[224:227], v[18:21]
	v_mfma_f32_16x16x32_bf16 v[6:9], v[176:179], v[232:235], v[6:9]
	v_mfma_f32_16x16x32_bf16 v[2:5], v[184:187], v[232:235], v[2:5]
	s_setprio 0
	s_setprio 1
	v_mfma_f32_16x16x32_bf16 v[54:57], v[180:183], v[212:215], v[54:57]
	v_mfma_f32_16x16x32_bf16 v[50:53], v[204:207], v[212:215], v[50:53]
	v_mfma_f32_16x16x32_bf16 v[38:41], v[180:183], v[220:223], v[38:41]
	v_mfma_f32_16x16x32_bf16 v[34:37], v[204:207], v[220:223], v[34:37]
	v_mfma_f32_16x16x32_bf16 v[22:25], v[180:183], v[228:231], v[22:25]
	v_mfma_f32_16x16x32_bf16 v[18:21], v[204:207], v[228:231], v[18:21]
	v_mfma_f32_16x16x32_bf16 v[6:9], v[180:183], v[236:239], v[6:9]
	v_mfma_f32_16x16x32_bf16 v[2:5], v[204:207], v[236:239], v[2:5]
	s_setprio 0
	s_barrier
	s_add_i32 s47, 0, 0x18000
	s_add_i32 s76, 0, 0x1c000
	v_add_u32_e32 v172, s47, v143
	v_add_u32_e32 v203, s76, v143
	ds_read_b128 v[156:159], v172
	ds_read_b128 v[164:167], v172 offset:1024
	ds_read_b128 v[168:171], v172 offset:2048
	ds_read_b128 v[172:175], v172 offset:3072
	ds_read_b128 v[176:179], v203
	ds_read_b128 v[180:183], v203 offset:1024
	ds_read_b128 v[184:187], v203 offset:2048
	ds_read_b128 v[204:207], v203 offset:3072
	s_add_u32 s62, s62, 0x200000
	s_addc_u32 s63, s63, 0
	s_mov_b32 m0, s57
	v_lshl_add_u64 v[246:247], s[62:63], 0, v[150:151]
	ds_read_b128 v[208:211], v163 offset:32768
	ds_read_b128 v[212:215], v163 offset:33792
	ds_read_b128 v[216:219], v163 offset:34816
	ds_read_b128 v[220:223], v163 offset:35840
	ds_read_b128 v[224:227], v163 offset:36864
	ds_read_b128 v[228:231], v163 offset:37888
	ds_read_b128 v[232:235], v163 offset:38912
	ds_read_b128 v[236:239], v163 offset:39936
	global_load_lds_dwordx4 v[246:247], off
	v_lshl_add_u64 v[246:247], s[62:63], 0, v[146:147]
	s_mov_b32 m0, s67
	s_nop 0
	global_load_lds_dwordx4 v[246:247], off
	s_waitcnt vmcnt(8)
	s_waitcnt lgkmcnt(0)
	s_barrier
	s_setprio 1
	s_waitcnt lgkmcnt(0)
	v_mfma_f32_16x16x32_bf16 v[126:129], v[156:159], v[208:211], v[126:129]
	v_mfma_f32_16x16x32_bf16 v[122:125], v[168:171], v[208:211], v[122:125]
	v_mfma_f32_16x16x32_bf16 v[110:113], v[156:159], v[216:219], v[110:113]
	v_mfma_f32_16x16x32_bf16 v[106:109], v[168:171], v[216:219], v[106:109]
	v_mfma_f32_16x16x32_bf16 v[94:97], v[156:159], v[224:227], v[94:97]
	v_mfma_f32_16x16x32_bf16 v[90:93], v[168:171], v[224:227], v[90:93]
	v_mfma_f32_16x16x32_bf16 v[78:81], v[156:159], v[232:235], v[78:81]
	v_mfma_f32_16x16x32_bf16 v[74:77], v[168:171], v[232:235], v[74:77]
	s_setprio 0
	s_setprio 1
	v_mfma_f32_16x16x32_bf16 v[126:129], v[164:167], v[212:215], v[126:129]
	v_mfma_f32_16x16x32_bf16 v[122:125], v[172:175], v[212:215], v[122:125]
	v_mfma_f32_16x16x32_bf16 v[110:113], v[164:167], v[220:223], v[110:113]
	v_mfma_f32_16x16x32_bf16 v[106:109], v[172:175], v[220:223], v[106:109]
	v_mfma_f32_16x16x32_bf16 v[94:97], v[164:167], v[228:231], v[94:97]
	v_mfma_f32_16x16x32_bf16 v[90:93], v[172:175], v[228:231], v[90:93]
	v_mfma_f32_16x16x32_bf16 v[78:81], v[164:167], v[236:239], v[78:81]
	v_mfma_f32_16x16x32_bf16 v[74:77], v[172:175], v[236:239], v[74:77]
	s_setprio 0
	s_setprio 1
	v_mfma_f32_16x16x32_bf16 v[118:121], v[176:179], v[208:211], v[118:121]
	v_mfma_f32_16x16x32_bf16 v[114:117], v[184:187], v[208:211], v[114:117]
	v_mfma_f32_16x16x32_bf16 v[102:105], v[176:179], v[216:219], v[102:105]
	v_mfma_f32_16x16x32_bf16 v[98:101], v[184:187], v[216:219], v[98:101]
	v_mfma_f32_16x16x32_bf16 v[86:89], v[176:179], v[224:227], v[86:89]
	v_mfma_f32_16x16x32_bf16 v[82:85], v[184:187], v[224:227], v[82:85]
	v_mfma_f32_16x16x32_bf16 v[70:73], v[176:179], v[232:235], v[70:73]
	v_mfma_f32_16x16x32_bf16 v[66:69], v[184:187], v[232:235], v[66:69]
	s_setprio 0
	s_setprio 1
	v_mfma_f32_16x16x32_bf16 v[118:121], v[180:183], v[212:215], v[118:121]
	v_mfma_f32_16x16x32_bf16 v[114:117], v[204:207], v[212:215], v[114:117]
	v_mfma_f32_16x16x32_bf16 v[102:105], v[180:183], v[220:223], v[102:105]
	v_mfma_f32_16x16x32_bf16 v[98:101], v[204:207], v[220:223], v[98:101]
	v_mfma_f32_16x16x32_bf16 v[86:89], v[180:183], v[228:231], v[86:89]
	v_mfma_f32_16x16x32_bf16 v[82:85], v[204:207], v[228:231], v[82:85]
	v_mfma_f32_16x16x32_bf16 v[70:73], v[180:183], v[236:239], v[70:73]
	v_mfma_f32_16x16x32_bf16 v[66:69], v[204:207], v[236:239], v[66:69]
	s_setprio 0
	s_barrier
; #define PG8_STAGE(bufoff, gbase, voff) do { _Pragma("unroll") for (int _i = 0; _i < 2; ++_i) \
;         __builtin_amdgcn_global_load_lds((const unsigned*)((const char*)(gbase) + (voff)[_i]), (PG8_LAS unsigned*)(lds + (bufoff) + ldsw + _i * 8192), 16, 0, 0); } while (0)
; #define PG8_LDA(dst, b, h) do { _Pragma("unroll") for (int m = 0; m < 4; ++m) _Pragma("unroll") for (int k = 0; k < 2; ++k) dst[m][k] = *(const PG8_LAS bf16x8*)(lds + PG8_SA(b, h) + aoff + m * 2048 + k * 1024); } while (0)
; #define PG8_MMA(ai, bj, At, Bt) do { __builtin_amdgcn_s_setprio(1); _Pragma("unroll") for (int m = 0; m < 4; ++m) _Pragma("unroll") for (int n = 0; n < 2; ++n) _Pragma("unroll") for (int k = 0; k < 2; ++k) \
;         acc[ai][bj][m][n] = __builtin_amdgcn_mfma_f32_16x16x32_bf16(Bt[n][k], At[m][k], acc[ai][bj][m][n], 0, 0, 0); __builtin_amdgcn_s_setprio(0); } while (0)
; #define PG8_WAIT_V(n) asm volatile("s_waitcnt vmcnt(" #n ")" ::: "memory")
; #define PG8_WAIT_L(n) asm volatile("s_waitcnt lgkmcnt(" #n ")" ::: "memory")
; #define PG8_BAR __builtin_amdgcn_s_barrier()
; #define PG8_SCHED __builtin_amdgcn_sched_barrier(0)
; template <class Epi, class Sched, bool ALIGN_EPI = false, bool SP2 = false>
; __device__ __forceinline__ void gemm_phase(PG8_LAS unsigned char* lds, const Gemm g, const Sched& S, const Epi& E) {
;     ...
;         for (int t = 0; t < nt; t += 2) {
;     ...
;             PG8_LDA(At, 1, 1); PG8_STAGE(PG8_SB(1, 0), b3, voffB); PG8_STAGE(PG8_SB(1, 1), b3 + hstep, voffB); PG8_STAGE(PG8_SA(1, 0), a3, voffA);
;             PG8_WAIT_V(8); PG8_WAIT_L(0); PG8_BAR; PG8_MMA(1, 0, At, B0); PG8_MMA(1, 1, At, B1); PG8_BAR; PG8_SCHED;
;     ...
;         if constexpr (ALIGN_EPI) { if (wr == 0) PG8_BAR; }
	s_add_i32 s47, s47, s4
	v_lshl_add_u64 v[160:161], v[160:161], 0, s[68:69]
	s_mov_b32 m0, s47
	ds_read_b128 v[208:211], v163 offset:49152
	ds_read_b128 v[212:215], v163 offset:50176
	ds_read_b128 v[216:219], v163 offset:51200
	ds_read_b128 v[220:223], v163 offset:52224
	ds_read_b128 v[224:227], v163 offset:53248
	ds_read_b128 v[228:231], v163 offset:54272
	ds_read_b128 v[232:235], v163 offset:55296
	ds_read_b128 v[236:239], v163 offset:56320
	global_load_lds_dwordx4 v[160:161], off
	s_add_i32 m0, s47, 0x2000
	s_add_u32 s18, s18, 0x200080
	v_lshl_add_u64 v[160:161], v[240:241], 0, s[68:69]
	s_addc_u32 s19, s19, 0
	s_add_i32 s47, s76, s4
	global_load_lds_dwordx4 v[160:161], off
	v_lshl_add_u64 v[160:161], s[18:19], 0, v[148:149]
	s_mov_b32 m0, s47
	s_nop 0
	global_load_lds_dwordx4 v[160:161], off
	v_lshl_add_u64 v[160:161], s[18:19], 0, v[144:145]
	s_add_i32 m0, s47, 0x2000
	s_nop 0
	global_load_lds_dwordx4 v[160:161], off
	v_lshl_add_u64 v[160:161], v[242:243], 0, s[68:69]
	s_mov_b32 m0, s1
	s_nop 0
	global_load_lds_dwordx4 v[160:161], off
	v_lshl_add_u64 v[160:161], v[244:245], 0, s[68:69]
	s_mov_b32 m0, s60
	s_nop 0
	global_load_lds_dwordx4 v[160:161], off
	s_waitcnt vmcnt(8)
	s_waitcnt lgkmcnt(0)
	s_barrier
	s_setprio 1
	s_waitcnt lgkmcnt(0)
	v_mfma_f32_16x16x32_bf16 v[62:65], v[156:159], v[208:211], v[62:65]
	v_mfma_f32_16x16x32_bf16 v[58:61], v[168:171], v[208:211], v[58:61]
	v_mfma_f32_16x16x32_bf16 v[46:49], v[156:159], v[216:219], v[46:49]
	v_mfma_f32_16x16x32_bf16 v[42:45], v[168:171], v[216:219], v[42:45]
	v_mfma_f32_16x16x32_bf16 v[30:33], v[156:159], v[224:227], v[30:33]
	v_mfma_f32_16x16x32_bf16 v[26:29], v[168:171], v[224:227], v[26:29]
	v_mfma_f32_16x16x32_bf16 v[14:17], v[156:159], v[232:235], v[14:17]
	v_mfma_f32_16x16x32_bf16 v[10:13], v[168:171], v[232:235], v[10:13]
	s_setprio 0
	s_setprio 1
	v_mfma_f32_16x16x32_bf16 v[62:65], v[164:167], v[212:215], v[62:65]
	v_mfma_f32_16x16x32_bf16 v[58:61], v[172:175], v[212:215], v[58:61]
	v_mfma_f32_16x16x32_bf16 v[46:49], v[164:167], v[220:223], v[46:49]
	v_mfma_f32_16x16x32_bf16 v[42:45], v[172:175], v[220:223], v[42:45]
	v_mfma_f32_16x16x32_bf16 v[30:33], v[164:167], v[228:231], v[30:33]
	v_mfma_f32_16x16x32_bf16 v[26:29], v[172:175], v[228:231], v[26:29]
	v_mfma_f32_16x16x32_bf16 v[14:17], v[164:167], v[236:239], v[14:17]
	v_mfma_f32_16x16x32_bf16 v[10:13], v[172:175], v[236:239], v[10:13]
	s_setprio 0
	s_setprio 1
	v_mfma_f32_16x16x32_bf16 v[54:57], v[176:179], v[208:211], v[54:57]
	v_mfma_f32_16x16x32_bf16 v[50:53], v[184:187], v[208:211], v[50:53]
	v_mfma_f32_16x16x32_bf16 v[38:41], v[176:179], v[216:219], v[38:41]
	v_mfma_f32_16x16x32_bf16 v[34:37], v[184:187], v[216:219], v[34:37]
	v_mfma_f32_16x16x32_bf16 v[22:25], v[176:179], v[224:227], v[22:25]
	v_mfma_f32_16x16x32_bf16 v[18:21], v[184:187], v[224:227], v[18:21]
	v_mfma_f32_16x16x32_bf16 v[6:9], v[176:179], v[232:235], v[6:9]
	v_mfma_f32_16x16x32_bf16 v[2:5], v[184:187], v[232:235], v[2:5]
	s_setprio 0
	s_setprio 1
	v_mfma_f32_16x16x32_bf16 v[54:57], v[180:183], v[212:215], v[54:57]
	v_mfma_f32_16x16x32_bf16 v[50:53], v[204:207], v[212:215], v[50:53]
	v_mfma_f32_16x16x32_bf16 v[38:41], v[180:183], v[220:223], v[38:41]
	v_mfma_f32_16x16x32_bf16 v[34:37], v[204:207], v[220:223], v[34:37]
	v_mfma_f32_16x16x32_bf16 v[22:25], v[180:183], v[228:231], v[22:25]
	v_mfma_f32_16x16x32_bf16 v[18:21], v[204:207], v[228:231], v[18:21]
	v_mfma_f32_16x16x32_bf16 v[6:9], v[180:183], v[236:239], v[6:9]
	v_mfma_f32_16x16x32_bf16 v[2:5], v[204:207], v[236:239], v[2:5]
	s_setprio 0
	s_barrier
	s_add_i32 s46, s46, 2
	s_add_u32 s58, s58, 0x100
	s_addc_u32 s59, s59, 0
	s_add_u32 s78, s78, 0x100
	s_addc_u32 s79, s79, 0
	s_cmpk_gt_u32 s46, 0x7d
	s_cbranch_scc0 .LBB0_36
	s_and_b64 vcc, exec, s[12:13]
	s_cbranch_vccz .LBB0_39
	s_barrier

; #define PG8_STAGE(bufoff, gbase, voff) do { _Pragma("unroll") for (int _i = 0; _i < 2; ++_i) \
;         __builtin_amdgcn_global_load_lds((const unsigned*)((const char*)(gbase) + (voff)[_i]), (PG8_LAS unsigned*)(lds + (bufoff) + ldsw + _i * 8192), 16, 0, 0); } while (0)
; #define PG8_LDA(dst, b, h) do { _Pragma("unroll") for (int m = 0; m < 4; ++m) _Pragma("unroll") for (int k = 0; k < 2; ++k) dst[m][k] = *(const PG8_LAS bf16x8*)(lds + PG8_SA(b, h) + aoff + m * 2048 + k * 1024); } while (0)
; #define PG8_LDB(dst, b, h) do { _Pragma("unroll") for (int n = 0; n < 2; ++n) _Pragma("unroll") for (int k = 0; k < 2; ++k) dst[n][k] = *(const PG8_LAS bf16x8*)(lds + PG8_SB(b, h) + boff + n * 2048 + k * 1024); } while (0)
; #define PG8_MMA(ai, bj, At, Bt) do { __builtin_amdgcn_s_setprio(1); _Pragma("unroll") for (int m = 0; m < 4; ++m) _Pragma("unroll") for (int n = 0; n < 2; ++n) _Pragma("unroll") for (int k = 0; k < 2; ++k) \
;         acc[ai][bj][m][n] = __builtin_amdgcn_mfma_f32_16x16x32_bf16(Bt[n][k], At[m][k], acc[ai][bj][m][n], 0, 0, 0); __builtin_amdgcn_s_setprio(0); } while (0)
; #define PG8_WAIT_V(n) asm volatile("s_waitcnt vmcnt(" #n ")" ::: "memory")
; #define PG8_WAIT_L(n) asm volatile("s_waitcnt lgkmcnt(" #n ")" ::: "memory")
; #define PG8_BAR __builtin_amdgcn_s_barrier()
; #define PG8_SCHED __builtin_amdgcn_sched_barrier(0)
; template <class Epi, class Sched, bool ALIGN_EPI = false, bool SP2 = false>
; __device__ __forceinline__ void gemm_phase(PG8_LAS unsigned char* lds, const Gemm g, const Sched& S, const Epi& E) {
;     ...
;             if constexpr (SP2) {
;             PG8_LDB(B0, 0, 0); PG8_LDB(B1, 0, 1); PG8_SCHED; PG8_LDA(At, 0, 0); PG8_STAGE(PG8_SA(1, 1), a1 + hstep, voffA);
;             PG8_WAIT_V(8); PG8_WAIT_L(0); PG8_BAR; PG8_MMA(0, 0, At, B0); PG8_MMA(0, 1, At, B1); PG8_BAR; PG8_SCHED;
;             PG8_LDA(At, 0, 1); PG8_STAGE(PG8_SB(0, 0), b2, voffB); PG8_STAGE(PG8_SB(0, 1), b2 + hstep, voffB); PG8_STAGE(PG8_SA(0, 0), a2, voffA);
;             PG8_WAIT_V(8); PG8_WAIT_L(0); PG8_BAR; PG8_MMA(1, 0, At, B0); PG8_MMA(1, 1, At, B1); PG8_BAR; PG8_SCHED;
.LBB0_76:
	s_add_u32 s18, s0, 0xfff80080
	s_addc_u32 s19, s1, -1
	s_add_i32 s47, 0, 0x10000
	s_cmp_eq_u32 s46, 28
	s_cselect_b32 s59, s60, s19
	s_cselect_b32 s58, s73, s18
	v_add_u32_e32 v158, s47, v143
	s_cselect_b32 s19, s45, s79
	s_cselect_b32 s18, s84, s78
	s_add_i32 s80, 0, 0x14000
	ds_read_b128 v[162:165], v158
	ds_read_b128 v[166:169], v158 offset:1024
	ds_read_b128 v[170:173], v158 offset:2048
	ds_read_b128 v[174:177], v158 offset:3072
	v_add_u32_e32 v158, s80, v143
	ds_read_b128 v[178:181], v158
	ds_read_b128 v[182:185], v158 offset:1024
	ds_read_b128 v[204:207], v158 offset:2048
	ds_read_b128 v[208:211], v158 offset:3072
	v_lshl_add_u64 v[158:159], s[0:1], 0, v[154:155]
	s_add_i32 m0, s62, 0xc000
	ds_read_b128 v[212:215], v161
	ds_read_b128 v[216:219], v161 offset:1024
	ds_read_b128 v[220:223], v161 offset:2048
	ds_read_b128 v[224:227], v161 offset:3072
	ds_read_b128 v[228:231], v161 offset:4096
	ds_read_b128 v[232:235], v161 offset:5120
	ds_read_b128 v[236:239], v161 offset:6144
	ds_read_b128 v[240:243], v161 offset:7168
	global_load_lds_dwordx4 v[158:159], off
	v_lshl_add_u64 v[158:159], s[0:1], 0, v[156:157]
	s_add_i32 m0, s62, 0xe000
	s_nop 0
	global_load_lds_dwordx4 v[158:159], off
	s_waitcnt vmcnt(8)
	s_waitcnt lgkmcnt(0)
	s_barrier
	s_setprio 1
	s_waitcnt lgkmcnt(0)
	v_mfma_f32_16x16x32_bf16 v[126:129], v[162:165], v[212:215], v[126:129]
	v_mfma_f32_16x16x32_bf16 v[122:125], v[170:173], v[212:215], v[122:125]
	v_mfma_f32_16x16x32_bf16 v[110:113], v[162:165], v[220:223], v[110:113]
	v_mfma_f32_16x16x32_bf16 v[106:109], v[170:173], v[220:223], v[106:109]
	v_mfma_f32_16x16x32_bf16 v[94:97], v[162:165], v[228:231], v[94:97]
	v_mfma_f32_16x16x32_bf16 v[90:93], v[170:173], v[228:231], v[90:93]
	v_mfma_f32_16x16x32_bf16 v[78:81], v[162:165], v[236:239], v[78:81]
	v_mfma_f32_16x16x32_bf16 v[74:77], v[170:173], v[236:239], v[74:77]
	s_setprio 0
	s_setprio 1
	v_mfma_f32_16x16x32_bf16 v[126:129], v[166:169], v[216:219], v[126:129]
	v_mfma_f32_16x16x32_bf16 v[122:125], v[174:177], v[216:219], v[122:125]
	v_mfma_f32_16x16x32_bf16 v[110:113], v[166:169], v[224:227], v[110:113]
	v_mfma_f32_16x16x32_bf16 v[106:109], v[174:177], v[224:227], v[106:109]
	v_mfma_f32_16x16x32_bf16 v[94:97], v[166:169], v[232:235], v[94:97]
	v_mfma_f32_16x16x32_bf16 v[90:93], v[174:177], v[232:235], v[90:93]
	v_mfma_f32_16x16x32_bf16 v[78:81], v[166:169], v[240:243], v[78:81]
	v_mfma_f32_16x16x32_bf16 v[74:77], v[174:177], v[240:243], v[74:77]
	s_setprio 0
	s_setprio 1
	v_mfma_f32_16x16x32_bf16 v[118:121], v[178:181], v[212:215], v[118:121]
	v_mfma_f32_16x16x32_bf16 v[114:117], v[204:207], v[212:215], v[114:117]
	v_mfma_f32_16x16x32_bf16 v[102:105], v[178:181], v[220:223], v[102:105]
	v_mfma_f32_16x16x32_bf16 v[98:101], v[204:207], v[220:223], v[98:101]
	v_mfma_f32_16x16x32_bf16 v[86:89], v[178:181], v[228:231], v[86:89]
	v_mfma_f32_16x16x32_bf16 v[82:85], v[204:207], v[228:231], v[82:85]
	v_mfma_f32_16x16x32_bf16 v[70:73], v[178:181], v[236:239], v[70:73]
	v_mfma_f32_16x16x32_bf16 v[66:69], v[204:207], v[236:239], v[66:69]
	s_setprio 0
	s_setprio 1
	v_mfma_f32_16x16x32_bf16 v[118:121], v[182:185], v[216:219], v[118:121]
	v_mfma_f32_16x16x32_bf16 v[114:117], v[208:211], v[216:219], v[114:117]
	v_mfma_f32_16x16x32_bf16 v[102:105], v[182:185], v[224:227], v[102:105]
	v_mfma_f32_16x16x32_bf16 v[98:101], v[208:211], v[224:227], v[98:101]
	v_mfma_f32_16x16x32_bf16 v[86:89], v[182:185], v[232:235], v[86:89]
	v_mfma_f32_16x16x32_bf16 v[82:85], v[208:211], v[232:235], v[82:85]
	v_mfma_f32_16x16x32_bf16 v[70:73], v[182:185], v[240:243], v[70:73]
	v_mfma_f32_16x16x32_bf16 v[66:69], v[208:211], v[240:243], v[66:69]
	s_setprio 0
	s_barrier
	s_add_i32 s47, s47, s54
	v_lshl_add_u64 v[158:159], s[18:19], 0, v[148:149]
	s_mov_b32 m0, s47
	ds_read_b128 v[212:215], v161 offset:16384
	ds_read_b128 v[216:219], v161 offset:17408
	ds_read_b128 v[220:223], v161 offset:18432
	ds_read_b128 v[224:227], v161 offset:19456
	ds_read_b128 v[228:231], v161 offset:20480
	ds_read_b128 v[232:235], v161 offset:21504
	ds_read_b128 v[236:239], v161 offset:22528
	ds_read_b128 v[240:243], v161 offset:23552
	global_load_lds_dwordx4 v[158:159], off
	s_add_i32 m0, s47, 0x2000
	s_add_u32 s76, s18, 0x80000
	v_lshl_add_u64 v[186:187], s[18:19], 0, v[144:145]
	s_addc_u32 s77, s19, 0
	s_add_i32 s47, s80, s54
	global_load_lds_dwordx4 v[186:187], off
	v_lshl_add_u64 v[244:245], s[76:77], 0, v[148:149]
	s_mov_b32 m0, s47
	v_lshl_add_u64 v[246:247], s[58:59], 0, v[146:147]
	global_load_lds_dwordx4 v[244:245], off
	v_lshl_add_u64 v[244:245], s[76:77], 0, v[144:145]
	s_add_i32 m0, s47, 0x2000
	s_nop 0
	global_load_lds_dwordx4 v[244:245], off
	v_lshl_add_u64 v[244:245], s[58:59], 0, v[150:151]
	s_mov_b32 m0, s62
	s_nop 0
	global_load_lds_dwordx4 v[244:245], off
	s_mov_b32 m0, s63
	s_nop 0
	global_load_lds_dwordx4 v[246:247], off
	s_waitcnt vmcnt(8)
	s_waitcnt lgkmcnt(0)
	s_barrier
; #define PG8_STAGE(bufoff, gbase, voff) do { _Pragma("unroll") for (int _i = 0; _i < 2; ++_i) \
;         __builtin_amdgcn_global_load_lds((const unsigned*)((const char*)(gbase) + (voff)[_i]), (PG8_LAS unsigned*)(lds + (bufoff) + ldsw + _i * 8192), 16, 0, 0); } while (0)
; #define PG8_LDA(dst, b, h) do { _Pragma("unroll") for (int m = 0; m < 4; ++m) _Pragma("unroll") for (int k = 0; k < 2; ++k) dst[m][k] = *(const PG8_LAS bf16x8*)(lds + PG8_SA(b, h) + aoff + m * 2048 + k * 1024); } while (0)
; #define PG8_LDB(dst, b, h) do { _Pragma("unroll") for (int n = 0; n < 2; ++n) _Pragma("unroll") for (int k = 0; k < 2; ++k) dst[n][k] = *(const PG8_LAS bf16x8*)(lds + PG8_SB(b, h) + boff + n * 2048 + k * 1024); } while (0)
; #define PG8_MMA(ai, bj, At, Bt) do { __builtin_amdgcn_s_setprio(1); _Pragma("unroll") for (int m = 0; m < 4; ++m) _Pragma("unroll") for (int n = 0; n < 2; ++n) _Pragma("unroll") for (int k = 0; k < 2; ++k) \
;         acc[ai][bj][m][n] = __builtin_amdgcn_mfma_f32_16x16x32_bf16(Bt[n][k], At[m][k], acc[ai][bj][m][n], 0, 0, 0); __builtin_amdgcn_s_setprio(0); } while (0)
; #define PG8_WAIT_V(n) asm volatile("s_waitcnt vmcnt(" #n ")" ::: "memory")
; #define PG8_WAIT_L(n) asm volatile("s_waitcnt lgkmcnt(" #n ")" ::: "memory")
; #define PG8_BAR __builtin_amdgcn_s_barrier()
; #define PG8_SCHED __builtin_amdgcn_sched_barrier(0)
; template <class Epi, class Sched, bool ALIGN_EPI = false, bool SP2 = false>
; __device__ __forceinline__ void gemm_phase(PG8_LAS unsigned char* lds, const Gemm g, const Sched& S, const Epi& E) {
;     ...
;             PG8_WAIT_V(8); PG8_WAIT_L(0); PG8_BAR; PG8_MMA(1, 0, At, B0); PG8_MMA(1, 1, At, B1); PG8_BAR; PG8_SCHED;
;             PG8_LDB(B0, 1, 0); PG8_LDB(B1, 1, 1); PG8_SCHED; PG8_LDA(At, 1, 0); PG8_STAGE(PG8_SA(0, 1), a2 + hstep, voffA);
;             PG8_WAIT_V(8); PG8_WAIT_L(0); PG8_BAR; PG8_MMA(0, 0, At, B0); PG8_MMA(0, 1, At, B1); PG8_BAR; PG8_SCHED;
	s_setprio 1
	s_waitcnt lgkmcnt(0)
	v_mfma_f32_16x16x32_bf16 v[62:65], v[162:165], v[212:215], v[62:65]
	v_mfma_f32_16x16x32_bf16 v[58:61], v[170:173], v[212:215], v[58:61]
	v_mfma_f32_16x16x32_bf16 v[46:49], v[162:165], v[220:223], v[46:49]
	v_mfma_f32_16x16x32_bf16 v[42:45], v[170:173], v[220:223], v[42:45]
	v_mfma_f32_16x16x32_bf16 v[30:33], v[162:165], v[228:231], v[30:33]
	v_mfma_f32_16x16x32_bf16 v[26:29], v[170:173], v[228:231], v[26:29]
	v_mfma_f32_16x16x32_bf16 v[14:17], v[162:165], v[236:239], v[14:17]
	v_mfma_f32_16x16x32_bf16 v[10:13], v[170:173], v[236:239], v[10:13]
	s_setprio 0
	s_setprio 1
	v_mfma_f32_16x16x32_bf16 v[62:65], v[166:169], v[216:219], v[62:65]
	v_mfma_f32_16x16x32_bf16 v[58:61], v[174:177], v[216:219], v[58:61]
	v_mfma_f32_16x16x32_bf16 v[46:49], v[166:169], v[224:227], v[46:49]
	v_mfma_f32_16x16x32_bf16 v[42:45], v[174:177], v[224:227], v[42:45]
	v_mfma_f32_16x16x32_bf16 v[30:33], v[166:169], v[232:235], v[30:33]
	v_mfma_f32_16x16x32_bf16 v[26:29], v[174:177], v[232:235], v[26:29]
	v_mfma_f32_16x16x32_bf16 v[14:17], v[166:169], v[240:243], v[14:17]
	v_mfma_f32_16x16x32_bf16 v[10:13], v[174:177], v[240:243], v[10:13]
	s_setprio 0
	s_setprio 1
	v_mfma_f32_16x16x32_bf16 v[54:57], v[178:181], v[212:215], v[54:57]
	v_mfma_f32_16x16x32_bf16 v[50:53], v[204:207], v[212:215], v[50:53]
	v_mfma_f32_16x16x32_bf16 v[38:41], v[178:181], v[220:223], v[38:41]
	v_mfma_f32_16x16x32_bf16 v[34:37], v[204:207], v[220:223], v[34:37]
	v_mfma_f32_16x16x32_bf16 v[22:25], v[178:181], v[228:231], v[22:25]
	v_mfma_f32_16x16x32_bf16 v[18:21], v[204:207], v[228:231], v[18:21]
	v_mfma_f32_16x16x32_bf16 v[6:9], v[178:181], v[236:239], v[6:9]
	v_mfma_f32_16x16x32_bf16 v[2:5], v[204:207], v[236:239], v[2:5]
	s_setprio 0
	s_setprio 1
	v_mfma_f32_16x16x32_bf16 v[54:57], v[182:185], v[216:219], v[54:57]
	v_mfma_f32_16x16x32_bf16 v[50:53], v[208:211], v[216:219], v[50:53]
	v_mfma_f32_16x16x32_bf16 v[38:41], v[182:185], v[224:227], v[38:41]
	v_mfma_f32_16x16x32_bf16 v[34:37], v[208:211], v[224:227], v[34:37]
	v_mfma_f32_16x16x32_bf16 v[22:25], v[182:185], v[232:235], v[22:25]
	v_mfma_f32_16x16x32_bf16 v[18:21], v[208:211], v[232:235], v[18:21]
	v_mfma_f32_16x16x32_bf16 v[6:9], v[182:185], v[240:243], v[6:9]
	v_mfma_f32_16x16x32_bf16 v[2:5], v[208:211], v[240:243], v[2:5]
	s_setprio 0
	s_barrier
	s_add_i32 s47, 0, 0x18000
	s_add_i32 s76, 0, 0x1c000
	v_add_u32_e32 v174, s47, v143
	v_add_u32_e32 v203, s76, v143
	ds_read_b128 v[162:165], v174
	ds_read_b128 v[166:169], v174 offset:1024
	ds_read_b128 v[170:173], v174 offset:2048
	ds_read_b128 v[174:177], v174 offset:3072
	ds_read_b128 v[178:181], v203
	ds_read_b128 v[182:185], v203 offset:1024
	ds_read_b128 v[204:207], v203 offset:2048
	ds_read_b128 v[208:211], v203 offset:3072
	s_add_u32 s58, s58, 0x80000
	s_addc_u32 s59, s59, 0
	s_mov_b32 m0, s67
	v_lshl_add_u64 v[248:249], s[58:59], 0, v[150:151]
	ds_read_b128 v[212:215], v161 offset:32768
	ds_read_b128 v[216:219], v161 offset:33792
	ds_read_b128 v[220:223], v161 offset:34816
	ds_read_b128 v[224:227], v161 offset:35840
	ds_read_b128 v[228:231], v161 offset:36864
	ds_read_b128 v[232:235], v161 offset:37888
	ds_read_b128 v[236:239], v161 offset:38912
	ds_read_b128 v[240:243], v161 offset:39936
	global_load_lds_dwordx4 v[248:249], off
	v_lshl_add_u64 v[248:249], s[58:59], 0, v[146:147]
	s_mov_b32 m0, s4
	s_nop 0
	global_load_lds_dwordx4 v[248:249], off
	s_waitcnt vmcnt(8)
	s_waitcnt lgkmcnt(0)
	s_barrier
	s_setprio 1
	s_waitcnt lgkmcnt(0)
	v_mfma_f32_16x16x32_bf16 v[126:129], v[162:165], v[212:215], v[126:129]
	v_mfma_f32_16x16x32_bf16 v[122:125], v[170:173], v[212:215], v[122:125]
	v_mfma_f32_16x16x32_bf16 v[110:113], v[162:165], v[220:223], v[110:113]
	v_mfma_f32_16x16x32_bf16 v[106:109], v[170:173], v[220:223], v[106:109]
	v_mfma_f32_16x16x32_bf16 v[94:97], v[162:165], v[228:231], v[94:97]
	v_mfma_f32_16x16x32_bf16 v[90:93], v[170:173], v[228:231], v[90:93]
	v_mfma_f32_16x16x32_bf16 v[78:81], v[162:165], v[236:239], v[78:81]
	v_mfma_f32_16x16x32_bf16 v[74:77], v[170:173], v[236:239], v[74:77]
	s_setprio 0
	s_setprio 1
	v_mfma_f32_16x16x32_bf16 v[126:129], v[166:169], v[216:219], v[126:129]
	v_mfma_f32_16x16x32_bf16 v[122:125], v[174:177], v[216:219], v[122:125]
	v_mfma_f32_16x16x32_bf16 v[110:113], v[166:169], v[224:227], v[110:113]
	v_mfma_f32_16x16x32_bf16 v[106:109], v[174:177], v[224:227], v[106:109]
	v_mfma_f32_16x16x32_bf16 v[94:97], v[166:169], v[232:235], v[94:97]
	v_mfma_f32_16x16x32_bf16 v[90:93], v[174:177], v[232:235], v[90:93]
	v_mfma_f32_16x16x32_bf16 v[78:81], v[166:169], v[240:243], v[78:81]
	v_mfma_f32_16x16x32_bf16 v[74:77], v[174:177], v[240:243], v[74:77]
	s_setprio 0
	s_setprio 1
	v_mfma_f32_16x16x32_bf16 v[118:121], v[178:181], v[212:215], v[118:121]
	v_mfma_f32_16x16x32_bf16 v[114:117], v[204:207], v[212:215], v[114:117]
	v_mfma_f32_16x16x32_bf16 v[102:105], v[178:181], v[220:223], v[102:105]
	v_mfma_f32_16x16x32_bf16 v[98:101], v[204:207], v[220:223], v[98:101]
	v_mfma_f32_16x16x32_bf16 v[86:89], v[178:181], v[228:231], v[86:89]
	v_mfma_f32_16x16x32_bf16 v[82:85], v[204:207], v[228:231], v[82:85]
	v_mfma_f32_16x16x32_bf16 v[70:73], v[178:181], v[236:239], v[70:73]
	v_mfma_f32_16x16x32_bf16 v[66:69], v[204:207], v[236:239], v[66:69]
	s_setprio 0
	s_setprio 1
	v_mfma_f32_16x16x32_bf16 v[118:121], v[182:185], v[216:219], v[118:121]
	v_mfma_f32_16x16x32_bf16 v[114:117], v[208:211], v[216:219], v[114:117]
	v_mfma_f32_16x16x32_bf16 v[102:105], v[182:185], v[224:227], v[102:105]
	v_mfma_f32_16x16x32_bf16 v[98:101], v[208:211], v[224:227], v[98:101]
	v_mfma_f32_16x16x32_bf16 v[86:89], v[182:185], v[232:235], v[86:89]
	v_mfma_f32_16x16x32_bf16 v[82:85], v[208:211], v[232:235], v[82:85]
	v_mfma_f32_16x16x32_bf16 v[70:73], v[182:185], v[240:243], v[70:73]
	v_mfma_f32_16x16x32_bf16 v[66:69], v[208:211], v[240:243], v[66:69]
	s_setprio 0
	s_barrier
; #define PG8_STAGE(bufoff, gbase, voff) do { _Pragma("unroll") for (int _i = 0; _i < 2; ++_i) \
;         __builtin_amdgcn_global_load_lds((const unsigned*)((const char*)(gbase) + (voff)[_i]), (PG8_LAS unsigned*)(lds + (bufoff) + ldsw + _i * 8192), 16, 0, 0); } while (0)
; #define PG8_LDA(dst, b, h) do { _Pragma("unroll") for (int m = 0; m < 4; ++m) _Pragma("unroll") for (int k = 0; k < 2; ++k) dst[m][k] = *(const PG8_LAS bf16x8*)(lds + PG8_SA(b, h) + aoff + m * 2048 + k * 1024); } while (0)
; #define PG8_MMA(ai, bj, At, Bt) do { __builtin_amdgcn_s_setprio(1); _Pragma("unroll") for (int m = 0; m < 4; ++m) _Pragma("unroll") for (int n = 0; n < 2; ++n) _Pragma("unroll") for (int k = 0; k < 2; ++k) \
;         acc[ai][bj][m][n] = __builtin_amdgcn_mfma_f32_16x16x32_bf16(Bt[n][k], At[m][k], acc[ai][bj][m][n], 0, 0, 0); __builtin_amdgcn_s_setprio(0); } while (0)
; #define PG8_WAIT_V(n) asm volatile("s_waitcnt vmcnt(" #n ")" ::: "memory")
; #define PG8_WAIT_L(n) asm volatile("s_waitcnt lgkmcnt(" #n ")" ::: "memory")
; #define PG8_BAR __builtin_amdgcn_s_barrier()
; #define PG8_SCHED __builtin_amdgcn_sched_barrier(0)
; template <class Epi, class Sched, bool ALIGN_EPI = false, bool SP2 = false>
; __device__ __forceinline__ void gemm_phase(PG8_LAS unsigned char* lds, const Gemm g, const Sched& S, const Epi& E) {
;     ...
;         for (int t = 0; t < nt; t += 2) {
;     ...
;             PG8_LDA(At, 1, 1); PG8_STAGE(PG8_SB(1, 0), b3, voffB); PG8_STAGE(PG8_SB(1, 1), b3 + hstep, voffB); PG8_STAGE(PG8_SA(1, 0), a3, voffA);
;             PG8_WAIT_V(8); PG8_WAIT_L(0); PG8_BAR; PG8_MMA(1, 0, At, B0); PG8_MMA(1, 1, At, B1); PG8_BAR; PG8_SCHED;
;     ...
;         if constexpr (ALIGN_EPI) { if (wr == 0) PG8_BAR; }
	s_add_i32 s47, s47, s54
	v_lshl_add_u64 v[158:159], v[158:159], 0, s[68:69]
	s_mov_b32 m0, s47
	ds_read_b128 v[212:215], v161 offset:49152
	ds_read_b128 v[216:219], v161 offset:50176
	ds_read_b128 v[220:223], v161 offset:51200
	ds_read_b128 v[224:227], v161 offset:52224
	ds_read_b128 v[228:231], v161 offset:53248
	ds_read_b128 v[232:235], v161 offset:54272
	ds_read_b128 v[236:239], v161 offset:55296
	ds_read_b128 v[240:243], v161 offset:56320
	global_load_lds_dwordx4 v[158:159], off
	s_add_i32 m0, s47, 0x2000
	s_add_u32 s18, s18, 0x80080
	v_lshl_add_u64 v[158:159], v[186:187], 0, s[68:69]
	s_addc_u32 s19, s19, 0
	s_add_i32 s47, s76, s54
	global_load_lds_dwordx4 v[158:159], off
	v_lshl_add_u64 v[158:159], s[18:19], 0, v[148:149]
	s_mov_b32 m0, s47
	s_nop 0
	global_load_lds_dwordx4 v[158:159], off
	v_lshl_add_u64 v[158:159], s[18:19], 0, v[144:145]
	s_add_i32 m0, s47, 0x2000
	s_nop 0
	global_load_lds_dwordx4 v[158:159], off
	v_lshl_add_u64 v[158:159], v[244:245], 0, s[68:69]
	s_mov_b32 m0, s5
	s_nop 0
	global_load_lds_dwordx4 v[158:159], off
	v_lshl_add_u64 v[158:159], v[246:247], 0, s[68:69]
	s_mov_b32 m0, s57
	s_nop 0
	global_load_lds_dwordx4 v[158:159], off
	s_waitcnt vmcnt(8)
	s_waitcnt lgkmcnt(0)
	s_barrier
	s_setprio 1
	s_waitcnt lgkmcnt(0)
	v_mfma_f32_16x16x32_bf16 v[62:65], v[162:165], v[212:215], v[62:65]
	v_mfma_f32_16x16x32_bf16 v[58:61], v[170:173], v[212:215], v[58:61]
	v_mfma_f32_16x16x32_bf16 v[46:49], v[162:165], v[220:223], v[46:49]
	v_mfma_f32_16x16x32_bf16 v[42:45], v[170:173], v[220:223], v[42:45]
	v_mfma_f32_16x16x32_bf16 v[30:33], v[162:165], v[228:231], v[30:33]
	v_mfma_f32_16x16x32_bf16 v[26:29], v[170:173], v[228:231], v[26:29]
	v_mfma_f32_16x16x32_bf16 v[14:17], v[162:165], v[236:239], v[14:17]
	v_mfma_f32_16x16x32_bf16 v[10:13], v[170:173], v[236:239], v[10:13]
	s_setprio 0
	s_setprio 1
	v_mfma_f32_16x16x32_bf16 v[62:65], v[166:169], v[216:219], v[62:65]
	v_mfma_f32_16x16x32_bf16 v[58:61], v[174:177], v[216:219], v[58:61]
	v_mfma_f32_16x16x32_bf16 v[46:49], v[166:169], v[224:227], v[46:49]
	v_mfma_f32_16x16x32_bf16 v[42:45], v[174:177], v[224:227], v[42:45]
	v_mfma_f32_16x16x32_bf16 v[30:33], v[166:169], v[232:235], v[30:33]
	v_mfma_f32_16x16x32_bf16 v[26:29], v[174:177], v[232:235], v[26:29]
	v_mfma_f32_16x16x32_bf16 v[14:17], v[166:169], v[240:243], v[14:17]
	v_mfma_f32_16x16x32_bf16 v[10:13], v[174:177], v[240:243], v[10:13]
	s_setprio 0
	s_setprio 1
	v_mfma_f32_16x16x32_bf16 v[54:57], v[178:181], v[212:215], v[54:57]
	v_mfma_f32_16x16x32_bf16 v[50:53], v[204:207], v[212:215], v[50:53]
	v_mfma_f32_16x16x32_bf16 v[38:41], v[178:181], v[220:223], v[38:41]
	v_mfma_f32_16x16x32_bf16 v[34:37], v[204:207], v[220:223], v[34:37]
	v_mfma_f32_16x16x32_bf16 v[22:25], v[178:181], v[228:231], v[22:25]
	v_mfma_f32_16x16x32_bf16 v[18:21], v[204:207], v[228:231], v[18:21]
	v_mfma_f32_16x16x32_bf16 v[6:9], v[178:181], v[236:239], v[6:9]
	v_mfma_f32_16x16x32_bf16 v[2:5], v[204:207], v[236:239], v[2:5]
	s_setprio 0
	s_setprio 1
	v_mfma_f32_16x16x32_bf16 v[54:57], v[182:185], v[216:219], v[54:57]
	v_mfma_f32_16x16x32_bf16 v[50:53], v[208:211], v[216:219], v[50:53]
	v_mfma_f32_16x16x32_bf16 v[38:41], v[182:185], v[224:227], v[38:41]
	v_mfma_f32_16x16x32_bf16 v[34:37], v[208:211], v[224:227], v[34:37]
	v_mfma_f32_16x16x32_bf16 v[22:25], v[182:185], v[232:235], v[22:25]
	v_mfma_f32_16x16x32_bf16 v[18:21], v[208:211], v[232:235], v[18:21]
	v_mfma_f32_16x16x32_bf16 v[6:9], v[182:185], v[240:243], v[6:9]
	v_mfma_f32_16x16x32_bf16 v[2:5], v[208:211], v[240:243], v[2:5]
	s_setprio 0
	s_barrier
	s_add_i32 s46, s46, 2
	s_add_u32 s0, s0, 0x100
	s_addc_u32 s1, s1, 0
	s_add_u32 s78, s78, 0x100
	s_addc_u32 s79, s79, 0
	s_cmp_gt_u32 s46, 29
	s_cbranch_scc0 .LBB0_76
	s_and_b64 vcc, exec, s[42:43]
	s_cbranch_vccz .LBB0_79
	s_barrier

; #define PG8_STAGE(bufoff, gbase, voff) do { _Pragma("unroll") for (int _i = 0; _i < 2; ++_i) \
;         __builtin_amdgcn_global_load_lds((const unsigned*)((const char*)(gbase) + (voff)[_i]), (PG8_LAS unsigned*)(lds + (bufoff) + ldsw + _i * 8192), 16, 0, 0); } while (0)
; #define PG8_LDA(dst, b, h) do { _Pragma("unroll") for (int m = 0; m < 4; ++m) _Pragma("unroll") for (int k = 0; k < 2; ++k) dst[m][k] = *(const PG8_LAS bf16x8*)(lds + PG8_SA(b, h) + aoff + m * 2048 + k * 1024); } while (0)
; #define PG8_LDB(dst, b, h) do { _Pragma("unroll") for (int n = 0; n < 2; ++n) _Pragma("unroll") for (int k = 0; k < 2; ++k) dst[n][k] = *(const PG8_LAS bf16x8*)(lds + PG8_SB(b, h) + boff + n * 2048 + k * 1024); } while (0)
; #define PG8_MMA(ai, bj, At, Bt) do { __builtin_amdgcn_s_setprio(1); _Pragma("unroll") for (int m = 0; m < 4; ++m) _Pragma("unroll") for (int n = 0; n < 2; ++n) _Pragma("unroll") for (int k = 0; k < 2; ++k) \
;         acc[ai][bj][m][n] = __builtin_amdgcn_mfma_f32_16x16x32_bf16(Bt[n][k], At[m][k], acc[ai][bj][m][n], 0, 0, 0); __builtin_amdgcn_s_setprio(0); } while (0)
; #define PG8_WAIT_V(n) asm volatile("s_waitcnt vmcnt(" #n ")" ::: "memory")
; #define PG8_WAIT_L(n) asm volatile("s_waitcnt lgkmcnt(" #n ")" ::: "memory")
; #define PG8_BAR __builtin_amdgcn_s_barrier()
; #define PG8_SCHED __builtin_amdgcn_sched_barrier(0)
; template <class Epi, class Sched, bool ALIGN_EPI = false, bool SP2 = false>
; __device__ __forceinline__ void gemm_phase(PG8_LAS unsigned char* lds, const Gemm g, const Sched& S, const Epi& E) {
;     ...
;             if constexpr (SP2) {
;             PG8_LDB(B0, 0, 0); PG8_LDB(B1, 0, 1); PG8_SCHED; PG8_LDA(At, 0, 0); PG8_STAGE(PG8_SA(1, 1), a1 + hstep, voffA);
;             PG8_WAIT_V(8); PG8_WAIT_L(0); PG8_BAR; PG8_MMA(0, 0, At, B0); PG8_MMA(0, 1, At, B1); PG8_BAR; PG8_SCHED;
;             PG8_LDA(At, 0, 1); PG8_STAGE(PG8_SB(0, 0), b2, voffB); PG8_STAGE(PG8_SB(0, 1), b2 + hstep, voffB); PG8_STAGE(PG8_SA(0, 0), a2, voffA);
;             PG8_WAIT_V(8); PG8_WAIT_L(0); PG8_BAR; PG8_MMA(1, 0, At, B0); PG8_MMA(1, 1, At, B1); PG8_BAR; PG8_SCHED;
.LBB0_98:
	s_add_u32 s40, vcc_lo, 0xfff80080
	s_addc_u32 s41, vcc_hi, -1
	s_add_i32 s47, 0, 0x10000
	s_cmp_eq_u32 s46, 28
	s_cselect_b32 s59, s97, s41
	s_cselect_b32 s58, s84, s40
	s_cselect_b32 s41, s85, s79
	s_cselect_b32 s40, s95, s78
	s_add_i32 s80, 0, 0x14000
	v_add_u32_e32 v170, s47, v143
	v_add_u32_e32 v186, s80, v143
	ds_read_b128 v[156:159], v170
	ds_read_b128 v[162:165], v170 offset:1024
	ds_read_b128 v[166:169], v170 offset:2048
	ds_read_b128 v[170:173], v170 offset:3072
	ds_read_b128 v[174:177], v186
	ds_read_b128 v[178:181], v186 offset:1024
	ds_read_b128 v[182:185], v186 offset:2048
	ds_read_b128 v[204:207], v186 offset:3072
	v_lshl_add_u64 v[186:187], vcc, 0, v[152:153]
	s_add_i32 m0, s5, 0xc000
	ds_read_b128 v[208:211], v161
	ds_read_b128 v[212:215], v161 offset:1024
	ds_read_b128 v[216:219], v161 offset:2048
	ds_read_b128 v[220:223], v161 offset:3072
	ds_read_b128 v[224:227], v161 offset:4096
	ds_read_b128 v[228:231], v161 offset:5120
	ds_read_b128 v[232:235], v161 offset:6144
	ds_read_b128 v[236:239], v161 offset:7168
	global_load_lds_dwordx4 v[186:187], off
	v_lshl_add_u64 v[186:187], vcc, 0, v[154:155]
	s_add_i32 m0, s5, 0xe000
	s_nop 0
	global_load_lds_dwordx4 v[186:187], off
	s_waitcnt vmcnt(8)
	s_waitcnt lgkmcnt(0)
	s_barrier
	s_setprio 1
	s_waitcnt lgkmcnt(0)
	v_mfma_f32_16x16x32_bf16 v[126:129], v[156:159], v[208:211], v[126:129]
	v_mfma_f32_16x16x32_bf16 v[122:125], v[166:169], v[208:211], v[122:125]
	v_mfma_f32_16x16x32_bf16 v[110:113], v[156:159], v[216:219], v[110:113]
	v_mfma_f32_16x16x32_bf16 v[106:109], v[166:169], v[216:219], v[106:109]
	v_mfma_f32_16x16x32_bf16 v[94:97], v[156:159], v[224:227], v[94:97]
	v_mfma_f32_16x16x32_bf16 v[90:93], v[166:169], v[224:227], v[90:93]
	v_mfma_f32_16x16x32_bf16 v[78:81], v[156:159], v[232:235], v[78:81]
	v_mfma_f32_16x16x32_bf16 v[74:77], v[166:169], v[232:235], v[74:77]
	s_setprio 0
	s_setprio 1
	v_mfma_f32_16x16x32_bf16 v[126:129], v[162:165], v[212:215], v[126:129]
	v_mfma_f32_16x16x32_bf16 v[122:125], v[170:173], v[212:215], v[122:125]
	v_mfma_f32_16x16x32_bf16 v[110:113], v[162:165], v[220:223], v[110:113]
	v_mfma_f32_16x16x32_bf16 v[106:109], v[170:173], v[220:223], v[106:109]
	v_mfma_f32_16x16x32_bf16 v[94:97], v[162:165], v[228:231], v[94:97]
	v_mfma_f32_16x16x32_bf16 v[90:93], v[170:173], v[228:231], v[90:93]
	v_mfma_f32_16x16x32_bf16 v[78:81], v[162:165], v[236:239], v[78:81]
	v_mfma_f32_16x16x32_bf16 v[74:77], v[170:173], v[236:239], v[74:77]
	s_setprio 0
	s_setprio 1
	v_mfma_f32_16x16x32_bf16 v[118:121], v[174:177], v[208:211], v[118:121]
	v_mfma_f32_16x16x32_bf16 v[114:117], v[182:185], v[208:211], v[114:117]
	v_mfma_f32_16x16x32_bf16 v[102:105], v[174:177], v[216:219], v[102:105]
	v_mfma_f32_16x16x32_bf16 v[98:101], v[182:185], v[216:219], v[98:101]
	v_mfma_f32_16x16x32_bf16 v[86:89], v[174:177], v[224:227], v[86:89]
	v_mfma_f32_16x16x32_bf16 v[82:85], v[182:185], v[224:227], v[82:85]
	v_mfma_f32_16x16x32_bf16 v[70:73], v[174:177], v[232:235], v[70:73]
	v_mfma_f32_16x16x32_bf16 v[66:69], v[182:185], v[232:235], v[66:69]
	s_setprio 0
	s_setprio 1
	v_mfma_f32_16x16x32_bf16 v[118:121], v[178:181], v[212:215], v[118:121]
	v_mfma_f32_16x16x32_bf16 v[114:117], v[204:207], v[212:215], v[114:117]
	v_mfma_f32_16x16x32_bf16 v[102:105], v[178:181], v[220:223], v[102:105]
	v_mfma_f32_16x16x32_bf16 v[98:101], v[204:207], v[220:223], v[98:101]
	v_mfma_f32_16x16x32_bf16 v[86:89], v[178:181], v[228:231], v[86:89]
	v_mfma_f32_16x16x32_bf16 v[82:85], v[204:207], v[228:231], v[82:85]
	v_mfma_f32_16x16x32_bf16 v[70:73], v[178:181], v[236:239], v[70:73]
	v_mfma_f32_16x16x32_bf16 v[66:69], v[204:207], v[236:239], v[66:69]
	s_setprio 0
	s_barrier
	s_add_i32 s47, s47, s4
	v_lshl_add_u64 v[186:187], s[40:41], 0, v[148:149]
	s_mov_b32 m0, s47
	ds_read_b128 v[208:211], v161 offset:16384
	ds_read_b128 v[212:215], v161 offset:17408
	ds_read_b128 v[216:219], v161 offset:18432
	ds_read_b128 v[220:223], v161 offset:19456
	ds_read_b128 v[224:227], v161 offset:20480
	ds_read_b128 v[228:231], v161 offset:21504
	ds_read_b128 v[232:235], v161 offset:22528
	ds_read_b128 v[236:239], v161 offset:23552
	global_load_lds_dwordx4 v[186:187], off
	s_add_i32 m0, s47, 0x2000
	s_add_u32 s76, s40, 0x80000
	v_lshl_add_u64 v[240:241], s[40:41], 0, v[144:145]
	s_addc_u32 s77, s41, 0
	s_add_i32 s47, s80, s4
	global_load_lds_dwordx4 v[240:241], off
	v_lshl_add_u64 v[242:243], s[76:77], 0, v[148:149]
	s_mov_b32 m0, s47
	v_lshl_add_u64 v[244:245], s[58:59], 0, v[146:147]
	global_load_lds_dwordx4 v[242:243], off
	v_lshl_add_u64 v[242:243], s[76:77], 0, v[144:145]
	s_add_i32 m0, s47, 0x2000
	s_nop 0
	global_load_lds_dwordx4 v[242:243], off
	v_lshl_add_u64 v[242:243], s[58:59], 0, v[150:151]
	s_mov_b32 m0, s5
	s_nop 0
	global_load_lds_dwordx4 v[242:243], off
	s_mov_b32 m0, s30
	s_nop 0
	global_load_lds_dwordx4 v[244:245], off
	s_waitcnt vmcnt(8)
	s_waitcnt lgkmcnt(0)
	s_barrier
; #define PG8_STAGE(bufoff, gbase, voff) do { _Pragma("unroll") for (int _i = 0; _i < 2; ++_i) \
;         __builtin_amdgcn_global_load_lds((const unsigned*)((const char*)(gbase) + (voff)[_i]), (PG8_LAS unsigned*)(lds + (bufoff) + ldsw + _i * 8192), 16, 0, 0); } while (0)
; #define PG8_LDA(dst, b, h) do { _Pragma("unroll") for (int m = 0; m < 4; ++m) _Pragma("unroll") for (int k = 0; k < 2; ++k) dst[m][k] = *(const PG8_LAS bf16x8*)(lds + PG8_SA(b, h) + aoff + m * 2048 + k * 1024); } while (0)
; #define PG8_LDB(dst, b, h) do { _Pragma("unroll") for (int n = 0; n < 2; ++n) _Pragma("unroll") for (int k = 0; k < 2; ++k) dst[n][k] = *(const PG8_LAS bf16x8*)(lds + PG8_SB(b, h) + boff + n * 2048 + k * 1024); } while (0)
; #define PG8_MMA(ai, bj, At, Bt) do { __builtin_amdgcn_s_setprio(1); _Pragma("unroll") for (int m = 0; m < 4; ++m) _Pragma("unroll") for (int n = 0; n < 2; ++n) _Pragma("unroll") for (int k = 0; k < 2; ++k) \
;         acc[ai][bj][m][n] = __builtin_amdgcn_mfma_f32_16x16x32_bf16(Bt[n][k], At[m][k], acc[ai][bj][m][n], 0, 0, 0); __builtin_amdgcn_s_setprio(0); } while (0)
; #define PG8_WAIT_V(n) asm volatile("s_waitcnt vmcnt(" #n ")" ::: "memory")
; #define PG8_WAIT_L(n) asm volatile("s_waitcnt lgkmcnt(" #n ")" ::: "memory")
; #define PG8_BAR __builtin_amdgcn_s_barrier()
; #define PG8_SCHED __builtin_amdgcn_sched_barrier(0)
; template <class Epi, class Sched, bool ALIGN_EPI = false, bool SP2 = false>
; __device__ __forceinline__ void gemm_phase(PG8_LAS unsigned char* lds, const Gemm g, const Sched& S, const Epi& E) {
;     ...
;             PG8_WAIT_V(8); PG8_WAIT_L(0); PG8_BAR; PG8_MMA(1, 0, At, B0); PG8_MMA(1, 1, At, B1); PG8_BAR; PG8_SCHED;
;             PG8_LDB(B0, 1, 0); PG8_LDB(B1, 1, 1); PG8_SCHED; PG8_LDA(At, 1, 0); PG8_STAGE(PG8_SA(0, 1), a2 + hstep, voffA);
;             PG8_WAIT_V(8); PG8_WAIT_L(0); PG8_BAR; PG8_MMA(0, 0, At, B0); PG8_MMA(0, 1, At, B1); PG8_BAR; PG8_SCHED;
	s_setprio 1
	s_waitcnt lgkmcnt(0)
	v_mfma_f32_16x16x32_bf16 v[62:65], v[156:159], v[208:211], v[62:65]
	v_mfma_f32_16x16x32_bf16 v[58:61], v[166:169], v[208:211], v[58:61]
	v_mfma_f32_16x16x32_bf16 v[46:49], v[156:159], v[216:219], v[46:49]
	v_mfma_f32_16x16x32_bf16 v[42:45], v[166:169], v[216:219], v[42:45]
	v_mfma_f32_16x16x32_bf16 v[30:33], v[156:159], v[224:227], v[30:33]
	v_mfma_f32_16x16x32_bf16 v[26:29], v[166:169], v[224:227], v[26:29]
	v_mfma_f32_16x16x32_bf16 v[14:17], v[156:159], v[232:235], v[14:17]
	v_mfma_f32_16x16x32_bf16 v[10:13], v[166:169], v[232:235], v[10:13]
	s_setprio 0
	s_setprio 1
	v_mfma_f32_16x16x32_bf16 v[62:65], v[162:165], v[212:215], v[62:65]
	v_mfma_f32_16x16x32_bf16 v[58:61], v[170:173], v[212:215], v[58:61]
	v_mfma_f32_16x16x32_bf16 v[46:49], v[162:165], v[220:223], v[46:49]
	v_mfma_f32_16x16x32_bf16 v[42:45], v[170:173], v[220:223], v[42:45]
	v_mfma_f32_16x16x32_bf16 v[30:33], v[162:165], v[228:231], v[30:33]
	v_mfma_f32_16x16x32_bf16 v[26:29], v[170:173], v[228:231], v[26:29]
	v_mfma_f32_16x16x32_bf16 v[14:17], v[162:165], v[236:239], v[14:17]
	v_mfma_f32_16x16x32_bf16 v[10:13], v[170:173], v[236:239], v[10:13]
	s_setprio 0
	s_setprio 1
	v_mfma_f32_16x16x32_bf16 v[54:57], v[174:177], v[208:211], v[54:57]
	v_mfma_f32_16x16x32_bf16 v[50:53], v[182:185], v[208:211], v[50:53]
	v_mfma_f32_16x16x32_bf16 v[38:41], v[174:177], v[216:219], v[38:41]
	v_mfma_f32_16x16x32_bf16 v[34:37], v[182:185], v[216:219], v[34:37]
	v_mfma_f32_16x16x32_bf16 v[22:25], v[174:177], v[224:227], v[22:25]
	v_mfma_f32_16x16x32_bf16 v[18:21], v[182:185], v[224:227], v[18:21]
	v_mfma_f32_16x16x32_bf16 v[6:9], v[174:177], v[232:235], v[6:9]
	v_mfma_f32_16x16x32_bf16 v[2:5], v[182:185], v[232:235], v[2:5]
	s_setprio 0
	s_setprio 1
	v_mfma_f32_16x16x32_bf16 v[54:57], v[178:181], v[212:215], v[54:57]
	v_mfma_f32_16x16x32_bf16 v[50:53], v[204:207], v[212:215], v[50:53]
	v_mfma_f32_16x16x32_bf16 v[38:41], v[178:181], v[220:223], v[38:41]
	v_mfma_f32_16x16x32_bf16 v[34:37], v[204:207], v[220:223], v[34:37]
	v_mfma_f32_16x16x32_bf16 v[22:25], v[178:181], v[228:231], v[22:25]
	v_mfma_f32_16x16x32_bf16 v[18:21], v[204:207], v[228:231], v[18:21]
	v_mfma_f32_16x16x32_bf16 v[6:9], v[178:181], v[236:239], v[6:9]
	v_mfma_f32_16x16x32_bf16 v[2:5], v[204:207], v[236:239], v[2:5]
	s_setprio 0
	s_barrier
	s_add_i32 s47, 0, 0x18000
	s_add_i32 s76, 0, 0x1c000
	v_add_u32_e32 v170, s47, v143
	v_add_u32_e32 v203, s76, v143
	ds_read_b128 v[156:159], v170
	ds_read_b128 v[162:165], v170 offset:1024
	ds_read_b128 v[166:169], v170 offset:2048
	ds_read_b128 v[170:173], v170 offset:3072
	ds_read_b128 v[174:177], v203
	ds_read_b128 v[178:181], v203 offset:1024
	ds_read_b128 v[182:185], v203 offset:2048
	ds_read_b128 v[204:207], v203 offset:3072
	s_add_u32 s58, s58, 0x80000
	s_addc_u32 s59, s59, 0
	s_mov_b32 m0, s34
	v_lshl_add_u64 v[246:247], s[58:59], 0, v[150:151]
	ds_read_b128 v[208:211], v161 offset:32768
	ds_read_b128 v[212:215], v161 offset:33792
	ds_read_b128 v[216:219], v161 offset:34816
	ds_read_b128 v[220:223], v161 offset:35840
	ds_read_b128 v[224:227], v161 offset:36864
	ds_read_b128 v[228:231], v161 offset:37888
	ds_read_b128 v[232:235], v161 offset:38912
	ds_read_b128 v[236:239], v161 offset:39936
	global_load_lds_dwordx4 v[246:247], off
	v_lshl_add_u64 v[246:247], s[58:59], 0, v[146:147]
	s_mov_b32 m0, s57
	s_nop 0
	global_load_lds_dwordx4 v[246:247], off
	s_waitcnt vmcnt(8)
	s_waitcnt lgkmcnt(0)
	s_barrier
	s_setprio 1
	s_waitcnt lgkmcnt(0)
	v_mfma_f32_16x16x32_bf16 v[126:129], v[156:159], v[208:211], v[126:129]
	v_mfma_f32_16x16x32_bf16 v[122:125], v[166:169], v[208:211], v[122:125]
	v_mfma_f32_16x16x32_bf16 v[110:113], v[156:159], v[216:219], v[110:113]
	v_mfma_f32_16x16x32_bf16 v[106:109], v[166:169], v[216:219], v[106:109]
	v_mfma_f32_16x16x32_bf16 v[94:97], v[156:159], v[224:227], v[94:97]
	v_mfma_f32_16x16x32_bf16 v[90:93], v[166:169], v[224:227], v[90:93]
	v_mfma_f32_16x16x32_bf16 v[78:81], v[156:159], v[232:235], v[78:81]
	v_mfma_f32_16x16x32_bf16 v[74:77], v[166:169], v[232:235], v[74:77]
	s_setprio 0
	s_setprio 1
	v_mfma_f32_16x16x32_bf16 v[126:129], v[162:165], v[212:215], v[126:129]
	v_mfma_f32_16x16x32_bf16 v[122:125], v[170:173], v[212:215], v[122:125]
	v_mfma_f32_16x16x32_bf16 v[110:113], v[162:165], v[220:223], v[110:113]
	v_mfma_f32_16x16x32_bf16 v[106:109], v[170:173], v[220:223], v[106:109]
	v_mfma_f32_16x16x32_bf16 v[94:97], v[162:165], v[228:231], v[94:97]
	v_mfma_f32_16x16x32_bf16 v[90:93], v[170:173], v[228:231], v[90:93]
	v_mfma_f32_16x16x32_bf16 v[78:81], v[162:165], v[236:239], v[78:81]
	v_mfma_f32_16x16x32_bf16 v[74:77], v[170:173], v[236:239], v[74:77]
	s_setprio 0
	s_setprio 1
	v_mfma_f32_16x16x32_bf16 v[118:121], v[174:177], v[208:211], v[118:121]
	v_mfma_f32_16x16x32_bf16 v[114:117], v[182:185], v[208:211], v[114:117]
	v_mfma_f32_16x16x32_bf16 v[102:105], v[174:177], v[216:219], v[102:105]
	v_mfma_f32_16x16x32_bf16 v[98:101], v[182:185], v[216:219], v[98:101]
	v_mfma_f32_16x16x32_bf16 v[86:89], v[174:177], v[224:227], v[86:89]
	v_mfma_f32_16x16x32_bf16 v[82:85], v[182:185], v[224:227], v[82:85]
	v_mfma_f32_16x16x32_bf16 v[70:73], v[174:177], v[232:235], v[70:73]
	v_mfma_f32_16x16x32_bf16 v[66:69], v[182:185], v[232:235], v[66:69]
	s_setprio 0
	s_setprio 1
	v_mfma_f32_16x16x32_bf16 v[118:121], v[178:181], v[212:215], v[118:121]
	v_mfma_f32_16x16x32_bf16 v[114:117], v[204:207], v[212:215], v[114:117]
	v_mfma_f32_16x16x32_bf16 v[102:105], v[178:181], v[220:223], v[102:105]
	v_mfma_f32_16x16x32_bf16 v[98:101], v[204:207], v[220:223], v[98:101]
	v_mfma_f32_16x16x32_bf16 v[86:89], v[178:181], v[228:231], v[86:89]
	v_mfma_f32_16x16x32_bf16 v[82:85], v[204:207], v[228:231], v[82:85]
	v_mfma_f32_16x16x32_bf16 v[70:73], v[178:181], v[236:239], v[70:73]
	v_mfma_f32_16x16x32_bf16 v[66:69], v[204:207], v[236:239], v[66:69]
	s_setprio 0
	s_barrier
; #define PG8_STAGE(bufoff, gbase, voff) do { _Pragma("unroll") for (int _i = 0; _i < 2; ++_i) \
;         __builtin_amdgcn_global_load_lds((const unsigned*)((const char*)(gbase) + (voff)[_i]), (PG8_LAS unsigned*)(lds + (bufoff) + ldsw + _i * 8192), 16, 0, 0); } while (0)
; #define PG8_LDA(dst, b, h) do { _Pragma("unroll") for (int m = 0; m < 4; ++m) _Pragma("unroll") for (int k = 0; k < 2; ++k) dst[m][k] = *(const PG8_LAS bf16x8*)(lds + PG8_SA(b, h) + aoff + m * 2048 + k * 1024); } while (0)
; #define PG8_MMA(ai, bj, At, Bt) do { __builtin_amdgcn_s_setprio(1); _Pragma("unroll") for (int m = 0; m < 4; ++m) _Pragma("unroll") for (int n = 0; n < 2; ++n) _Pragma("unroll") for (int k = 0; k < 2; ++k) \
;         acc[ai][bj][m][n] = __builtin_amdgcn_mfma_f32_16x16x32_bf16(Bt[n][k], At[m][k], acc[ai][bj][m][n], 0, 0, 0); __builtin_amdgcn_s_setprio(0); } while (0)
; #define PG8_WAIT_V(n) asm volatile("s_waitcnt vmcnt(" #n ")" ::: "memory")
; #define PG8_WAIT_L(n) asm volatile("s_waitcnt lgkmcnt(" #n ")" ::: "memory")
; #define PG8_BAR __builtin_amdgcn_s_barrier()
; #define PG8_SCHED __builtin_amdgcn_sched_barrier(0)
;     __device__ __forceinline__ void operator()(const f32x4 (&acc)[2][2][4][2], const Unit& u, int wr, int wc, int fr, int fq) const {
;         const int row0 = u.pm * BM + wr * 64 + fr, col0 = u.pn * BM + wc * 32 + 8 * fq;
; #pragma unroll
;         for (int ai = 0; ai < 2; ++ai)
; #pragma unroll
;             for (int m = 0; m < 4; ++m) { const size_t row = (size_t)(row0 + ai * HALF + m * 16); float ss = 0.f;
; #pragma unroll
;                 for (int bj = 0; bj < 2; ++bj) { const size_t off = row * DM + col0 + bj * HALF;
;                     f32x4 v0 = acc[ai][bj][m][0] + *(const f32x4*)(base + off), v1 = acc[ai][bj][m][1] + *(const f32x4*)(base + off + 4);
; template <class Epi, class Sched, bool ALIGN_EPI = false, bool SP2 = false>
; __device__ __forceinline__ void gemm_phase(PG8_LAS unsigned char* lds, const Gemm g, const Sched& S, const Epi& E) {
;     ...
;         for (int t = 0; t < nt; t += 2) {
;     ...
;             PG8_LDA(At, 1, 1); PG8_STAGE(PG8_SB(1, 0), b3, voffB); PG8_STAGE(PG8_SB(1, 1), b3 + hstep, voffB); PG8_STAGE(PG8_SA(1, 0), a3, voffA);
;             PG8_WAIT_V(8); PG8_WAIT_L(0); PG8_BAR; PG8_MMA(1, 0, At, B0); PG8_MMA(1, 1, At, B1); PG8_BAR; PG8_SCHED;
	s_add_i32 s47, s47, s4
	v_lshl_add_u64 v[186:187], v[186:187], 0, s[68:69]
	s_mov_b32 m0, s47
	ds_read_b128 v[208:211], v161 offset:49152
	ds_read_b128 v[212:215], v161 offset:50176
	ds_read_b128 v[216:219], v161 offset:51200
	ds_read_b128 v[220:223], v161 offset:52224
	ds_read_b128 v[224:227], v161 offset:53248
	ds_read_b128 v[228:231], v161 offset:54272
	ds_read_b128 v[232:235], v161 offset:55296
	ds_read_b128 v[236:239], v161 offset:56320
	global_load_lds_dwordx4 v[186:187], off
	s_add_i32 m0, s47, 0x2000
	s_add_u32 s40, s40, 0x80080
	v_lshl_add_u64 v[186:187], v[240:241], 0, s[68:69]
	s_addc_u32 s41, s41, 0
	s_add_i32 s47, s76, s4
	global_load_lds_dwordx4 v[186:187], off
	v_lshl_add_u64 v[186:187], s[40:41], 0, v[148:149]
	s_mov_b32 m0, s47
	s_nop 0
	global_load_lds_dwordx4 v[186:187], off
	v_lshl_add_u64 v[186:187], s[40:41], 0, v[144:145]
	s_add_i32 m0, s47, 0x2000
	s_nop 0
	global_load_lds_dwordx4 v[186:187], off
	v_lshl_add_u64 v[186:187], v[242:243], 0, s[68:69]
	s_mov_b32 m0, s67
	s_nop 0
	global_load_lds_dwordx4 v[186:187], off
	v_lshl_add_u64 v[186:187], v[244:245], 0, s[68:69]
	s_mov_b32 m0, s28
	s_nop 0
	global_load_lds_dwordx4 v[186:187], off
	s_waitcnt vmcnt(8)
	s_waitcnt lgkmcnt(0)
	s_barrier
	s_setprio 1
	s_waitcnt lgkmcnt(0)
	v_mfma_f32_16x16x32_bf16 v[62:65], v[156:159], v[208:211], v[62:65]
	v_mfma_f32_16x16x32_bf16 v[58:61], v[166:169], v[208:211], v[58:61]
	v_mfma_f32_16x16x32_bf16 v[46:49], v[156:159], v[216:219], v[46:49]
	v_mfma_f32_16x16x32_bf16 v[42:45], v[166:169], v[216:219], v[42:45]
	v_mfma_f32_16x16x32_bf16 v[30:33], v[156:159], v[224:227], v[30:33]
	v_mfma_f32_16x16x32_bf16 v[26:29], v[166:169], v[224:227], v[26:29]
	v_mfma_f32_16x16x32_bf16 v[14:17], v[156:159], v[232:235], v[14:17]
	v_mfma_f32_16x16x32_bf16 v[10:13], v[166:169], v[232:235], v[10:13]
	s_setprio 0
	s_setprio 1
	v_mfma_f32_16x16x32_bf16 v[62:65], v[162:165], v[212:215], v[62:65]
	v_mfma_f32_16x16x32_bf16 v[58:61], v[170:173], v[212:215], v[58:61]
	v_mfma_f32_16x16x32_bf16 v[46:49], v[162:165], v[220:223], v[46:49]
	v_mfma_f32_16x16x32_bf16 v[42:45], v[170:173], v[220:223], v[42:45]
	v_mfma_f32_16x16x32_bf16 v[30:33], v[162:165], v[228:231], v[30:33]
	v_mfma_f32_16x16x32_bf16 v[26:29], v[170:173], v[228:231], v[26:29]
	v_mfma_f32_16x16x32_bf16 v[14:17], v[162:165], v[236:239], v[14:17]
	v_mfma_f32_16x16x32_bf16 v[10:13], v[170:173], v[236:239], v[10:13]
	s_setprio 0
	s_setprio 1
	v_mfma_f32_16x16x32_bf16 v[54:57], v[174:177], v[208:211], v[54:57]
	v_mfma_f32_16x16x32_bf16 v[50:53], v[182:185], v[208:211], v[50:53]
	v_mfma_f32_16x16x32_bf16 v[38:41], v[174:177], v[216:219], v[38:41]
	v_mfma_f32_16x16x32_bf16 v[34:37], v[182:185], v[216:219], v[34:37]
	v_mfma_f32_16x16x32_bf16 v[22:25], v[174:177], v[224:227], v[22:25]
	v_mfma_f32_16x16x32_bf16 v[18:21], v[182:185], v[224:227], v[18:21]
	v_mfma_f32_16x16x32_bf16 v[6:9], v[174:177], v[232:235], v[6:9]
	v_mfma_f32_16x16x32_bf16 v[2:5], v[182:185], v[232:235], v[2:5]
	s_setprio 0
	s_setprio 1
	v_mfma_f32_16x16x32_bf16 v[54:57], v[178:181], v[212:215], v[54:57]
	v_mfma_f32_16x16x32_bf16 v[50:53], v[204:207], v[212:215], v[50:53]
	v_mfma_f32_16x16x32_bf16 v[38:41], v[178:181], v[220:223], v[38:41]
	v_mfma_f32_16x16x32_bf16 v[34:37], v[204:207], v[220:223], v[34:37]
	v_mfma_f32_16x16x32_bf16 v[22:25], v[178:181], v[228:231], v[22:25]
	v_mfma_f32_16x16x32_bf16 v[18:21], v[204:207], v[228:231], v[18:21]
	v_mfma_f32_16x16x32_bf16 v[6:9], v[178:181], v[236:239], v[6:9]
	v_mfma_f32_16x16x32_bf16 v[2:5], v[204:207], v[236:239], v[2:5]
	s_setprio 0
	s_barrier
	s_add_i32 s46, s46, 2
	s_add_u32 vcc_lo, vcc_lo, 0x100
	s_addc_u32 vcc_hi, vcc_hi, 0
	s_add_u32 s78, s78, 0x100
	s_addc_u32 s79, s79, 0
	s_cmp_gt_u32 s46, 29
	s_cbranch_scc0 .LBB0_98
	v_lshl_add_u32 v156, s73, 8, v1
	v_lshl_or_b32 v157, s54, 8, v160
	v_lshl_add_u32 v157, v156, 11, v157
	v_mov_b32_e32 v247, 0
	v_lshlrev_b32_e32 v246, 2, v157
	v_lshl_add_u64 v[162:163], s[8:9], 0, v[246:247]
	v_lshlrev_b32_e32 v246, 1, v157
	v_lshl_add_u64 v[244:245], s[70:71], 0, v[246:247]
	s_mov_b32 s41, 0
	global_load_dwordx4 v[164:167], v[162:163], off
	global_load_dwordx4 v[168:171], v[162:163], off offset:16
	global_load_dwordx4 v[172:175], v[162:163], off offset:512
	global_load_dwordx4 v[176:179], v[162:163], off offset:528
	s_mov_b32 s40, 0x20000
	v_lshl_add_u64 v[246:247], v[162:163], 0, s[40:41]
	global_load_dwordx4 v[180:183], v[246:247], off
	global_load_dwordx4 v[184:187], v[246:247], off offset:16
	global_load_dwordx4 v[204:207], v[246:247], off offset:512
	global_load_dwordx4 v[208:211], v[246:247], off offset:528
	s_mov_b32 s40, 0x40000
	v_lshl_add_u64 v[246:247], v[162:163], 0, s[40:41]
	global_load_dwordx4 v[212:215], v[246:247], off
	global_load_dwordx4 v[216:219], v[246:247], off offset:16
	global_load_dwordx4 v[220:223], v[246:247], off offset:512
	global_load_dwordx4 v[224:227], v[246:247], off offset:528
	s_mov_b32 s40, 0x60000
	v_lshl_add_u64 v[246:247], v[162:163], 0, s[40:41]
	global_load_dwordx4 v[228:231], v[246:247], off
	global_load_dwordx4 v[232:235], v[246:247], off offset:16
	global_load_dwordx4 v[236:239], v[246:247], off offset:512
	global_load_dwordx4 v[240:243], v[246:247], off offset:528
	s_and_b64 vcc, exec, s[36:37]
	s_cbranch_vccz .Lx1_nobar
	s_barrier

; #define PG8_STAGE(bufoff, gbase, voff) do { _Pragma("unroll") for (int _i = 0; _i < 2; ++_i) \
;         __builtin_amdgcn_global_load_lds((const unsigned*)((const char*)(gbase) + (voff)[_i]), (PG8_LAS unsigned*)(lds + (bufoff) + ldsw + _i * 8192), 16, 0, 0); } while (0)
; #define PG8_LDA(dst, b, h) do { _Pragma("unroll") for (int m = 0; m < 4; ++m) _Pragma("unroll") for (int k = 0; k < 2; ++k) dst[m][k] = *(const PG8_LAS bf16x8*)(lds + PG8_SA(b, h) + aoff + m * 2048 + k * 1024); } while (0)
; #define PG8_LDB(dst, b, h) do { _Pragma("unroll") for (int n = 0; n < 2; ++n) _Pragma("unroll") for (int k = 0; k < 2; ++k) dst[n][k] = *(const PG8_LAS bf16x8*)(lds + PG8_SB(b, h) + boff + n * 2048 + k * 1024); } while (0)
; #define PG8_MMA(ai, bj, At, Bt) do { __builtin_amdgcn_s_setprio(1); _Pragma("unroll") for (int m = 0; m < 4; ++m) _Pragma("unroll") for (int n = 0; n < 2; ++n) _Pragma("unroll") for (int k = 0; k < 2; ++k) \
;         acc[ai][bj][m][n] = __builtin_amdgcn_mfma_f32_16x16x32_bf16(Bt[n][k], At[m][k], acc[ai][bj][m][n], 0, 0, 0); __builtin_amdgcn_s_setprio(0); } while (0)
; #define PG8_WAIT_V(n) asm volatile("s_waitcnt vmcnt(" #n ")" ::: "memory")
; #define PG8_WAIT_L(n) asm volatile("s_waitcnt lgkmcnt(" #n ")" ::: "memory")
; #define PG8_BAR __builtin_amdgcn_s_barrier()
; #define PG8_SCHED __builtin_amdgcn_sched_barrier(0)
; template <class Epi, class Sched, bool ALIGN_EPI = false, bool SP2 = false>
; __device__ __forceinline__ void gemm_phase(PG8_LAS unsigned char* lds, const Gemm g, const Sched& S, const Epi& E) {
;     ...
;             if constexpr (SP2) {
;             PG8_LDB(B0, 0, 0); PG8_LDB(B1, 0, 1); PG8_SCHED; PG8_LDA(At, 0, 0); PG8_STAGE(PG8_SA(1, 1), a1 + hstep, voffA);
;             PG8_WAIT_V(8); PG8_WAIT_L(0); PG8_BAR; PG8_MMA(0, 0, At, B0); PG8_MMA(0, 1, At, B1); PG8_BAR; PG8_SCHED;
;             PG8_LDA(At, 0, 1); PG8_STAGE(PG8_SB(0, 0), b2, voffB); PG8_STAGE(PG8_SB(0, 1), b2 + hstep, voffB); PG8_STAGE(PG8_SA(0, 0), a2, voffA);
;             PG8_WAIT_V(8); PG8_WAIT_L(0); PG8_BAR; PG8_MMA(1, 0, At, B0); PG8_MMA(1, 1, At, B1); PG8_BAR; PG8_SCHED;
.LBB0_136:
	s_add_u32 s18, s58, 0xfffe0080
	s_addc_u32 s19, s59, -1
	s_add_i32 s46, 0, 0x10000
	s_cmp_eq_u32 s79, 4
	s_cselect_b32 s63, s37, s19
	s_cselect_b32 s62, s73, s18
	s_cselect_b32 s19, s11, s78
	s_cselect_b32 s18, s84, s85
	s_add_i32 s76, 0, 0x14000
	v_add_u32_e32 v172, s46, v1
	v_add_u32_e32 v203, s76, v1
	ds_read_b128 v[160:163], v172
	ds_read_b128 v[164:167], v172 offset:1024
	ds_read_b128 v[168:171], v172 offset:2048
	ds_read_b128 v[172:175], v172 offset:3072
	ds_read_b128 v[176:179], v203
	ds_read_b128 v[180:183], v203 offset:1024
	ds_read_b128 v[184:187], v203 offset:2048
	ds_read_b128 v[204:207], v203 offset:3072
	v_lshl_add_u64 v[240:241], s[58:59], 0, v[156:157]
	s_add_i32 m0, s5, 0xc000
	ds_read_b128 v[208:211], v143
	ds_read_b128 v[212:215], v143 offset:1024
	ds_read_b128 v[216:219], v143 offset:2048
	ds_read_b128 v[220:223], v143 offset:3072
	ds_read_b128 v[224:227], v143 offset:4096
	ds_read_b128 v[228:231], v143 offset:5120
	ds_read_b128 v[232:235], v143 offset:6144
	ds_read_b128 v[236:239], v143 offset:7168
	global_load_lds_dwordx4 v[240:241], off
	v_lshl_add_u64 v[240:241], s[58:59], 0, v[158:159]
	s_add_i32 m0, s5, 0xe000
	s_nop 0
	global_load_lds_dwordx4 v[240:241], off
	s_waitcnt vmcnt(8)
	s_waitcnt lgkmcnt(0)
	s_barrier
	s_setprio 1
	s_waitcnt lgkmcnt(0)
	v_mfma_f32_16x16x32_bf16 v[126:129], v[160:163], v[208:211], v[126:129]
	v_mfma_f32_16x16x32_bf16 v[122:125], v[168:171], v[208:211], v[122:125]
	v_mfma_f32_16x16x32_bf16 v[110:113], v[160:163], v[216:219], v[110:113]
	v_mfma_f32_16x16x32_bf16 v[106:109], v[168:171], v[216:219], v[106:109]
	v_mfma_f32_16x16x32_bf16 v[94:97], v[160:163], v[224:227], v[94:97]
	v_mfma_f32_16x16x32_bf16 v[90:93], v[168:171], v[224:227], v[90:93]
	v_mfma_f32_16x16x32_bf16 v[78:81], v[160:163], v[232:235], v[78:81]
	v_mfma_f32_16x16x32_bf16 v[74:77], v[168:171], v[232:235], v[74:77]
	s_setprio 0
	s_setprio 1
	v_mfma_f32_16x16x32_bf16 v[126:129], v[164:167], v[212:215], v[126:129]
	v_mfma_f32_16x16x32_bf16 v[122:125], v[172:175], v[212:215], v[122:125]
	v_mfma_f32_16x16x32_bf16 v[110:113], v[164:167], v[220:223], v[110:113]
	v_mfma_f32_16x16x32_bf16 v[106:109], v[172:175], v[220:223], v[106:109]
	v_mfma_f32_16x16x32_bf16 v[94:97], v[164:167], v[228:231], v[94:97]
	v_mfma_f32_16x16x32_bf16 v[90:93], v[172:175], v[228:231], v[90:93]
	v_mfma_f32_16x16x32_bf16 v[78:81], v[164:167], v[236:239], v[78:81]
	v_mfma_f32_16x16x32_bf16 v[74:77], v[172:175], v[236:239], v[74:77]
	s_setprio 0
	s_setprio 1
	v_mfma_f32_16x16x32_bf16 v[118:121], v[176:179], v[208:211], v[118:121]
	v_mfma_f32_16x16x32_bf16 v[114:117], v[184:187], v[208:211], v[114:117]
	v_mfma_f32_16x16x32_bf16 v[102:105], v[176:179], v[216:219], v[102:105]
	v_mfma_f32_16x16x32_bf16 v[98:101], v[184:187], v[216:219], v[98:101]
	v_mfma_f32_16x16x32_bf16 v[86:89], v[176:179], v[224:227], v[86:89]
	v_mfma_f32_16x16x32_bf16 v[82:85], v[184:187], v[224:227], v[82:85]
	v_mfma_f32_16x16x32_bf16 v[70:73], v[176:179], v[232:235], v[70:73]
	v_mfma_f32_16x16x32_bf16 v[66:69], v[184:187], v[232:235], v[66:69]
	s_setprio 0
	s_setprio 1
	v_mfma_f32_16x16x32_bf16 v[118:121], v[180:183], v[212:215], v[118:121]
	v_mfma_f32_16x16x32_bf16 v[114:117], v[204:207], v[212:215], v[114:117]
	v_mfma_f32_16x16x32_bf16 v[102:105], v[180:183], v[220:223], v[102:105]
	v_mfma_f32_16x16x32_bf16 v[98:101], v[204:207], v[220:223], v[98:101]
	v_mfma_f32_16x16x32_bf16 v[86:89], v[180:183], v[228:231], v[86:89]
	v_mfma_f32_16x16x32_bf16 v[82:85], v[204:207], v[228:231], v[82:85]
	v_mfma_f32_16x16x32_bf16 v[70:73], v[180:183], v[236:239], v[70:73]
	v_mfma_f32_16x16x32_bf16 v[66:69], v[204:207], v[236:239], v[66:69]
	s_setprio 0
	s_barrier
	s_add_i32 s46, s46, s4
	v_lshl_add_u64 v[240:241], s[18:19], 0, v[148:149]
	s_mov_b32 m0, s46
	ds_read_b128 v[208:211], v143 offset:16384
	ds_read_b128 v[212:215], v143 offset:17408
	ds_read_b128 v[216:219], v143 offset:18432
	ds_read_b128 v[220:223], v143 offset:19456
	ds_read_b128 v[224:227], v143 offset:20480
	ds_read_b128 v[228:231], v143 offset:21504
	ds_read_b128 v[232:235], v143 offset:22528
	ds_read_b128 v[236:239], v143 offset:23552
	global_load_lds_dwordx4 v[240:241], off
	s_add_i32 m0, s46, 0x2000
	s_add_u32 s46, s18, 0x20000
	v_lshl_add_u64 v[242:243], s[18:19], 0, v[144:145]
	s_addc_u32 s47, s19, 0
	s_add_i32 s76, s76, s4
	global_load_lds_dwordx4 v[242:243], off
	v_lshl_add_u64 v[244:245], s[46:47], 0, v[148:149]
	s_mov_b32 m0, s76
	v_lshl_add_u64 v[246:247], s[62:63], 0, v[146:147]
	global_load_lds_dwordx4 v[244:245], off
	v_lshl_add_u64 v[244:245], s[46:47], 0, v[144:145]
	s_add_i32 m0, s76, 0x2000
	s_nop 0
	global_load_lds_dwordx4 v[244:245], off
	v_lshl_add_u64 v[244:245], s[62:63], 0, v[150:151]
	s_mov_b32 m0, s5
	s_nop 0
	global_load_lds_dwordx4 v[244:245], off
	s_mov_b32 m0, s28
	s_nop 0
	global_load_lds_dwordx4 v[246:247], off
	s_waitcnt vmcnt(8)
	s_waitcnt lgkmcnt(0)
	s_barrier
; #define PG8_STAGE(bufoff, gbase, voff) do { _Pragma("unroll") for (int _i = 0; _i < 2; ++_i) \
;         __builtin_amdgcn_global_load_lds((const unsigned*)((const char*)(gbase) + (voff)[_i]), (PG8_LAS unsigned*)(lds + (bufoff) + ldsw + _i * 8192), 16, 0, 0); } while (0)
; #define PG8_LDA(dst, b, h) do { _Pragma("unroll") for (int m = 0; m < 4; ++m) _Pragma("unroll") for (int k = 0; k < 2; ++k) dst[m][k] = *(const PG8_LAS bf16x8*)(lds + PG8_SA(b, h) + aoff + m * 2048 + k * 1024); } while (0)
; #define PG8_LDB(dst, b, h) do { _Pragma("unroll") for (int n = 0; n < 2; ++n) _Pragma("unroll") for (int k = 0; k < 2; ++k) dst[n][k] = *(const PG8_LAS bf16x8*)(lds + PG8_SB(b, h) + boff + n * 2048 + k * 1024); } while (0)
; #define PG8_MMA(ai, bj, At, Bt) do { __builtin_amdgcn_s_setprio(1); _Pragma("unroll") for (int m = 0; m < 4; ++m) _Pragma("unroll") for (int n = 0; n < 2; ++n) _Pragma("unroll") for (int k = 0; k < 2; ++k) \
;         acc[ai][bj][m][n] = __builtin_amdgcn_mfma_f32_16x16x32_bf16(Bt[n][k], At[m][k], acc[ai][bj][m][n], 0, 0, 0); __builtin_amdgcn_s_setprio(0); } while (0)
; #define PG8_WAIT_V(n) asm volatile("s_waitcnt vmcnt(" #n ")" ::: "memory")
; #define PG8_WAIT_L(n) asm volatile("s_waitcnt lgkmcnt(" #n ")" ::: "memory")
; #define PG8_BAR __builtin_amdgcn_s_barrier()
; #define PG8_SCHED __builtin_amdgcn_sched_barrier(0)
; template <class Epi, class Sched, bool ALIGN_EPI = false, bool SP2 = false>
; __device__ __forceinline__ void gemm_phase(PG8_LAS unsigned char* lds, const Gemm g, const Sched& S, const Epi& E) {
;     ...
;             PG8_WAIT_V(8); PG8_WAIT_L(0); PG8_BAR; PG8_MMA(1, 0, At, B0); PG8_MMA(1, 1, At, B1); PG8_BAR; PG8_SCHED;
;             PG8_LDB(B0, 1, 0); PG8_LDB(B1, 1, 1); PG8_SCHED; PG8_LDA(At, 1, 0); PG8_STAGE(PG8_SA(0, 1), a2 + hstep, voffA);
;             PG8_WAIT_V(8); PG8_WAIT_L(0); PG8_BAR; PG8_MMA(0, 0, At, B0); PG8_MMA(0, 1, At, B1); PG8_BAR; PG8_SCHED;
	s_setprio 1
	s_waitcnt lgkmcnt(0)
	v_mfma_f32_16x16x32_bf16 v[62:65], v[160:163], v[208:211], v[62:65]
	v_mfma_f32_16x16x32_bf16 v[58:61], v[168:171], v[208:211], v[58:61]
	v_mfma_f32_16x16x32_bf16 v[46:49], v[160:163], v[216:219], v[46:49]
	v_mfma_f32_16x16x32_bf16 v[42:45], v[168:171], v[216:219], v[42:45]
	v_mfma_f32_16x16x32_bf16 v[30:33], v[160:163], v[224:227], v[30:33]
	v_mfma_f32_16x16x32_bf16 v[26:29], v[168:171], v[224:227], v[26:29]
	v_mfma_f32_16x16x32_bf16 v[14:17], v[160:163], v[232:235], v[14:17]
	v_mfma_f32_16x16x32_bf16 v[10:13], v[168:171], v[232:235], v[10:13]
	s_setprio 0
	s_setprio 1
	v_mfma_f32_16x16x32_bf16 v[62:65], v[164:167], v[212:215], v[62:65]
	v_mfma_f32_16x16x32_bf16 v[58:61], v[172:175], v[212:215], v[58:61]
	v_mfma_f32_16x16x32_bf16 v[46:49], v[164:167], v[220:223], v[46:49]
	v_mfma_f32_16x16x32_bf16 v[42:45], v[172:175], v[220:223], v[42:45]
	v_mfma_f32_16x16x32_bf16 v[30:33], v[164:167], v[228:231], v[30:33]
	v_mfma_f32_16x16x32_bf16 v[26:29], v[172:175], v[228:231], v[26:29]
	v_mfma_f32_16x16x32_bf16 v[14:17], v[164:167], v[236:239], v[14:17]
	v_mfma_f32_16x16x32_bf16 v[10:13], v[172:175], v[236:239], v[10:13]
	s_setprio 0
	s_setprio 1
	v_mfma_f32_16x16x32_bf16 v[54:57], v[176:179], v[208:211], v[54:57]
	v_mfma_f32_16x16x32_bf16 v[50:53], v[184:187], v[208:211], v[50:53]
	v_mfma_f32_16x16x32_bf16 v[38:41], v[176:179], v[216:219], v[38:41]
	v_mfma_f32_16x16x32_bf16 v[34:37], v[184:187], v[216:219], v[34:37]
	v_mfma_f32_16x16x32_bf16 v[22:25], v[176:179], v[224:227], v[22:25]
	v_mfma_f32_16x16x32_bf16 v[18:21], v[184:187], v[224:227], v[18:21]
	v_mfma_f32_16x16x32_bf16 v[6:9], v[176:179], v[232:235], v[6:9]
	v_mfma_f32_16x16x32_bf16 v[2:5], v[184:187], v[232:235], v[2:5]
	s_setprio 0
	s_setprio 1
	v_mfma_f32_16x16x32_bf16 v[54:57], v[180:183], v[212:215], v[54:57]
	v_mfma_f32_16x16x32_bf16 v[50:53], v[204:207], v[212:215], v[50:53]
	v_mfma_f32_16x16x32_bf16 v[38:41], v[180:183], v[220:223], v[38:41]
	v_mfma_f32_16x16x32_bf16 v[34:37], v[204:207], v[220:223], v[34:37]
	v_mfma_f32_16x16x32_bf16 v[22:25], v[180:183], v[228:231], v[22:25]
	v_mfma_f32_16x16x32_bf16 v[18:21], v[204:207], v[228:231], v[18:21]
	v_mfma_f32_16x16x32_bf16 v[6:9], v[180:183], v[236:239], v[6:9]
	v_mfma_f32_16x16x32_bf16 v[2:5], v[204:207], v[236:239], v[2:5]
	s_setprio 0
	s_barrier
	s_add_i32 s76, 0, 0x18000
	s_add_i32 s77, 0, 0x1c000
	v_add_u32_e32 v172, s76, v1
	v_add_u32_e32 v203, s77, v1
	ds_read_b128 v[160:163], v172
	ds_read_b128 v[164:167], v172 offset:1024
	ds_read_b128 v[168:171], v172 offset:2048
	ds_read_b128 v[172:175], v172 offset:3072
	ds_read_b128 v[176:179], v203
	ds_read_b128 v[180:183], v203 offset:1024
	ds_read_b128 v[184:187], v203 offset:2048
	ds_read_b128 v[204:207], v203 offset:3072
	s_add_u32 s46, s62, 0x20000
	s_addc_u32 s47, s63, 0
	s_mov_b32 m0, s30
	v_lshl_add_u64 v[248:249], s[46:47], 0, v[150:151]
	ds_read_b128 v[208:211], v143 offset:32768
	ds_read_b128 v[212:215], v143 offset:33792
	ds_read_b128 v[216:219], v143 offset:34816
	ds_read_b128 v[220:223], v143 offset:35840
	ds_read_b128 v[224:227], v143 offset:36864
	ds_read_b128 v[228:231], v143 offset:37888
	ds_read_b128 v[232:235], v143 offset:38912
	ds_read_b128 v[236:239], v143 offset:39936
	global_load_lds_dwordx4 v[248:249], off
	v_lshl_add_u64 v[248:249], s[46:47], 0, v[146:147]
	s_mov_b32 m0, s34
	s_nop 0
	global_load_lds_dwordx4 v[248:249], off
	s_waitcnt vmcnt(8)
	s_waitcnt lgkmcnt(0)
	s_barrier
	s_setprio 1
	s_waitcnt lgkmcnt(0)
	v_mfma_f32_16x16x32_bf16 v[126:129], v[160:163], v[208:211], v[126:129]
	v_mfma_f32_16x16x32_bf16 v[122:125], v[168:171], v[208:211], v[122:125]
	v_mfma_f32_16x16x32_bf16 v[110:113], v[160:163], v[216:219], v[110:113]
	v_mfma_f32_16x16x32_bf16 v[106:109], v[168:171], v[216:219], v[106:109]
	v_mfma_f32_16x16x32_bf16 v[94:97], v[160:163], v[224:227], v[94:97]
	v_mfma_f32_16x16x32_bf16 v[90:93], v[168:171], v[224:227], v[90:93]
	v_mfma_f32_16x16x32_bf16 v[78:81], v[160:163], v[232:235], v[78:81]
	v_mfma_f32_16x16x32_bf16 v[74:77], v[168:171], v[232:235], v[74:77]
	s_setprio 0
	s_setprio 1
	v_mfma_f32_16x16x32_bf16 v[126:129], v[164:167], v[212:215], v[126:129]
	v_mfma_f32_16x16x32_bf16 v[122:125], v[172:175], v[212:215], v[122:125]
	v_mfma_f32_16x16x32_bf16 v[110:113], v[164:167], v[220:223], v[110:113]
	v_mfma_f32_16x16x32_bf16 v[106:109], v[172:175], v[220:223], v[106:109]
	v_mfma_f32_16x16x32_bf16 v[94:97], v[164:167], v[228:231], v[94:97]
	v_mfma_f32_16x16x32_bf16 v[90:93], v[172:175], v[228:231], v[90:93]
	v_mfma_f32_16x16x32_bf16 v[78:81], v[164:167], v[236:239], v[78:81]
	v_mfma_f32_16x16x32_bf16 v[74:77], v[172:175], v[236:239], v[74:77]
	s_setprio 0
	s_setprio 1
	v_mfma_f32_16x16x32_bf16 v[118:121], v[176:179], v[208:211], v[118:121]
	v_mfma_f32_16x16x32_bf16 v[114:117], v[184:187], v[208:211], v[114:117]
	v_mfma_f32_16x16x32_bf16 v[102:105], v[176:179], v[216:219], v[102:105]
	v_mfma_f32_16x16x32_bf16 v[98:101], v[184:187], v[216:219], v[98:101]
	v_mfma_f32_16x16x32_bf16 v[86:89], v[176:179], v[224:227], v[86:89]
	v_mfma_f32_16x16x32_bf16 v[82:85], v[184:187], v[224:227], v[82:85]
	v_mfma_f32_16x16x32_bf16 v[70:73], v[176:179], v[232:235], v[70:73]
	v_mfma_f32_16x16x32_bf16 v[66:69], v[184:187], v[232:235], v[66:69]
	s_setprio 0
	s_setprio 1
	v_mfma_f32_16x16x32_bf16 v[118:121], v[180:183], v[212:215], v[118:121]
	v_mfma_f32_16x16x32_bf16 v[114:117], v[204:207], v[212:215], v[114:117]
	v_mfma_f32_16x16x32_bf16 v[102:105], v[180:183], v[220:223], v[102:105]
	v_mfma_f32_16x16x32_bf16 v[98:101], v[204:207], v[220:223], v[98:101]
	v_mfma_f32_16x16x32_bf16 v[86:89], v[180:183], v[228:231], v[86:89]
	v_mfma_f32_16x16x32_bf16 v[82:85], v[204:207], v[228:231], v[82:85]
	v_mfma_f32_16x16x32_bf16 v[70:73], v[180:183], v[236:239], v[70:73]
	v_mfma_f32_16x16x32_bf16 v[66:69], v[204:207], v[236:239], v[66:69]
	s_setprio 0
	s_barrier
; #define PG8_STAGE(bufoff, gbase, voff) do { _Pragma("unroll") for (int _i = 0; _i < 2; ++_i) \
;         __builtin_amdgcn_global_load_lds((const unsigned*)((const char*)(gbase) + (voff)[_i]), (PG8_LAS unsigned*)(lds + (bufoff) + ldsw + _i * 8192), 16, 0, 0); } while (0)
; #define PG8_LDA(dst, b, h) do { _Pragma("unroll") for (int m = 0; m < 4; ++m) _Pragma("unroll") for (int k = 0; k < 2; ++k) dst[m][k] = *(const PG8_LAS bf16x8*)(lds + PG8_SA(b, h) + aoff + m * 2048 + k * 1024); } while (0)
; #define PG8_MMA(ai, bj, At, Bt) do { __builtin_amdgcn_s_setprio(1); _Pragma("unroll") for (int m = 0; m < 4; ++m) _Pragma("unroll") for (int n = 0; n < 2; ++n) _Pragma("unroll") for (int k = 0; k < 2; ++k) \
;         acc[ai][bj][m][n] = __builtin_amdgcn_mfma_f32_16x16x32_bf16(Bt[n][k], At[m][k], acc[ai][bj][m][n], 0, 0, 0); __builtin_amdgcn_s_setprio(0); } while (0)
; #define PG8_WAIT_V(n) asm volatile("s_waitcnt vmcnt(" #n ")" ::: "memory")
; #define PG8_WAIT_L(n) asm volatile("s_waitcnt lgkmcnt(" #n ")" ::: "memory")
; #define PG8_BAR __builtin_amdgcn_s_barrier()
; #define PG8_SCHED __builtin_amdgcn_sched_barrier(0)
;     __device__ __forceinline__ void operator()(const f32x4 (&acc)[2][2][4][2], const Unit& u, int wr, int wc, int fr, int fq) const {
;         const int row0 = u.pm * BM + wr * 64 + fr, col0 = u.pn * BM + wc * 32 + 8 * fq;
;         const int tidn = (wr * 4 + wc) * 64 + fq * 16 + fr;
;         const u32x4* gp = (const u32x4*)G8 + (size_t)(u.pm * 16 + gsel + u.pn) * 8 * 512 + tidn;
;         u32x4* mp = M1 + (size_t)(u.pm * 8 + u.pn) * 16 * 512 + tidn;
;         constexpr float K255 = 1.0f / 255.0f;
; #pragma unroll
;         for (int ai = 0; ai < 2; ++ai)
; #pragma unroll
;             for (int m = 0; m < 4; ++m) { const size_t row = (size_t)(row0 + ai * HALF + m * 16);
;                 const u32x4 gw = gp[(ai * 4 + m) * 512];
; template <class Epi, class Sched, bool ALIGN_EPI = false, bool SP2 = false>
; __device__ __forceinline__ void gemm_phase(PG8_LAS unsigned char* lds, const Gemm g, const Sched& S, const Epi& E) {
;     ...
;             PG8_LDA(At, 1, 1); PG8_STAGE(PG8_SB(1, 0), b3, voffB); PG8_STAGE(PG8_SB(1, 1), b3 + hstep, voffB); PG8_STAGE(PG8_SA(1, 0), a3, voffA);
;             PG8_WAIT_V(8); PG8_WAIT_L(0); PG8_BAR; PG8_MMA(1, 0, At, B0); PG8_MMA(1, 1, At, B1); PG8_BAR; PG8_SCHED;
	s_add_i32 s46, s76, s4
	v_lshl_add_u64 v[240:241], v[240:241], 0, s[68:69]
	s_mov_b32 m0, s46
	ds_read_b128 v[208:211], v143 offset:49152
	ds_read_b128 v[212:215], v143 offset:50176
	ds_read_b128 v[216:219], v143 offset:51200
	ds_read_b128 v[220:223], v143 offset:52224
	ds_read_b128 v[224:227], v143 offset:53248
	ds_read_b128 v[228:231], v143 offset:54272
	ds_read_b128 v[232:235], v143 offset:55296
	ds_read_b128 v[236:239], v143 offset:56320
	global_load_lds_dwordx4 v[240:241], off
	s_add_i32 m0, s46, 0x2000
	s_add_u32 s18, s18, 0x20080
	v_lshl_add_u64 v[240:241], v[242:243], 0, s[68:69]
	s_addc_u32 s19, s19, 0
	s_add_i32 s46, s77, s4
	global_load_lds_dwordx4 v[240:241], off
	v_lshl_add_u64 v[240:241], s[18:19], 0, v[148:149]
	s_mov_b32 m0, s46
	s_nop 0
	global_load_lds_dwordx4 v[240:241], off
	v_lshl_add_u64 v[240:241], s[18:19], 0, v[144:145]
	s_add_i32 m0, s46, 0x2000
	s_nop 0
	global_load_lds_dwordx4 v[240:241], off
	v_lshl_add_u64 v[240:241], v[244:245], 0, s[68:69]
	s_mov_b32 m0, s54
	s_nop 0
	global_load_lds_dwordx4 v[240:241], off
	v_lshl_add_u64 v[240:241], v[246:247], 0, s[68:69]
	s_mov_b32 m0, s57
	s_nop 0
	global_load_lds_dwordx4 v[240:241], off
	s_waitcnt vmcnt(8)
	s_waitcnt lgkmcnt(0)
	s_barrier
	s_setprio 1
	s_waitcnt lgkmcnt(0)
	v_mfma_f32_16x16x32_bf16 v[62:65], v[160:163], v[208:211], v[62:65]
	v_mfma_f32_16x16x32_bf16 v[58:61], v[168:171], v[208:211], v[58:61]
	v_mfma_f32_16x16x32_bf16 v[46:49], v[160:163], v[216:219], v[46:49]
	v_mfma_f32_16x16x32_bf16 v[42:45], v[168:171], v[216:219], v[42:45]
	v_mfma_f32_16x16x32_bf16 v[30:33], v[160:163], v[224:227], v[30:33]
	v_mfma_f32_16x16x32_bf16 v[26:29], v[168:171], v[224:227], v[26:29]
	v_mfma_f32_16x16x32_bf16 v[14:17], v[160:163], v[232:235], v[14:17]
	v_mfma_f32_16x16x32_bf16 v[10:13], v[168:171], v[232:235], v[10:13]
	s_setprio 0
	s_setprio 1
	v_mfma_f32_16x16x32_bf16 v[62:65], v[164:167], v[212:215], v[62:65]
	v_mfma_f32_16x16x32_bf16 v[58:61], v[172:175], v[212:215], v[58:61]
	v_mfma_f32_16x16x32_bf16 v[46:49], v[164:167], v[220:223], v[46:49]
	v_mfma_f32_16x16x32_bf16 v[42:45], v[172:175], v[220:223], v[42:45]
	v_mfma_f32_16x16x32_bf16 v[30:33], v[164:167], v[228:231], v[30:33]
	v_mfma_f32_16x16x32_bf16 v[26:29], v[172:175], v[228:231], v[26:29]
	v_mfma_f32_16x16x32_bf16 v[14:17], v[164:167], v[236:239], v[14:17]
	v_mfma_f32_16x16x32_bf16 v[10:13], v[172:175], v[236:239], v[10:13]
	s_setprio 0
	s_setprio 1
	v_mfma_f32_16x16x32_bf16 v[54:57], v[176:179], v[208:211], v[54:57]
	v_mfma_f32_16x16x32_bf16 v[50:53], v[184:187], v[208:211], v[50:53]
	v_mfma_f32_16x16x32_bf16 v[38:41], v[176:179], v[216:219], v[38:41]
	v_mfma_f32_16x16x32_bf16 v[34:37], v[184:187], v[216:219], v[34:37]
	v_mfma_f32_16x16x32_bf16 v[22:25], v[176:179], v[224:227], v[22:25]
	v_mfma_f32_16x16x32_bf16 v[18:21], v[184:187], v[224:227], v[18:21]
	v_mfma_f32_16x16x32_bf16 v[6:9], v[176:179], v[232:235], v[6:9]
	v_mfma_f32_16x16x32_bf16 v[2:5], v[184:187], v[232:235], v[2:5]
	s_setprio 0
	s_setprio 1
	v_mfma_f32_16x16x32_bf16 v[54:57], v[180:183], v[212:215], v[54:57]
	v_mfma_f32_16x16x32_bf16 v[50:53], v[204:207], v[212:215], v[50:53]
	v_mfma_f32_16x16x32_bf16 v[38:41], v[180:183], v[220:223], v[38:41]
	v_mfma_f32_16x16x32_bf16 v[34:37], v[204:207], v[220:223], v[34:37]
	v_mfma_f32_16x16x32_bf16 v[22:25], v[180:183], v[228:231], v[22:25]
	v_mfma_f32_16x16x32_bf16 v[18:21], v[204:207], v[228:231], v[18:21]
	v_mfma_f32_16x16x32_bf16 v[6:9], v[180:183], v[236:239], v[6:9]
	v_mfma_f32_16x16x32_bf16 v[2:5], v[204:207], v[236:239], v[2:5]
	s_setprio 0
	s_barrier
	s_add_i32 s79, s79, 2
	s_add_u32 s58, s58, 0x100
	s_addc_u32 s59, s59, 0
	s_add_u32 s85, s85, 0x100
	s_addc_u32 s78, s78, 0
	s_cmp_gt_u32 s79, 5
	s_cbranch_scc0 .LBB0_136
	s_lshl_b32 s11, s67, 4
	s_add_i32 s18, s11, s86
	s_ashr_i32 s19, s18, 31
	s_lshl_b64 s[46:47], s[18:19], 16
	v_lshl_add_u64 v[162:163], v[152:153], 0, s[46:47]
	s_lshl_b32 s11, s67, 3
	s_sub_i32 s18, s18, s11
	s_ashr_i32 s19, s18, 31
	s_lshl_b64 s[18:19], s[18:19], 17
	v_lshl_add_u64 v[160:161], v[154:155], 0, s[18:19]
	s_mov_b32 s47, 0
	global_load_dwordx4 v[168:171], v[162:163], off
	s_mov_b32 s46, 0x2000
	v_lshl_add_u64 v[164:165], v[162:163], 0, s[46:47]
	global_load_dwordx4 v[172:175], v[164:165], off
	s_mov_b32 s46, 0x4000
	v_lshl_add_u64 v[164:165], v[162:163], 0, s[46:47]
	global_load_dwordx4 v[176:179], v[164:165], off
	s_mov_b32 s46, 0x6000
	v_lshl_add_u64 v[164:165], v[162:163], 0, s[46:47]
	global_load_dwordx4 v[180:183], v[164:165], off
	s_mov_b32 s46, 0x8000
	v_lshl_add_u64 v[164:165], v[162:163], 0, s[46:47]
	global_load_dwordx4 v[184:187], v[164:165], off
	s_mov_b32 s46, 0xa000
	v_lshl_add_u64 v[164:165], v[162:163], 0, s[46:47]
	global_load_dwordx4 v[204:207], v[164:165], off
	s_mov_b32 s46, 0xc000
	v_lshl_add_u64 v[164:165], v[162:163], 0, s[46:47]
	global_load_dwordx4 v[208:211], v[164:165], off
	s_mov_b32 s46, 0xe000
	v_lshl_add_u64 v[164:165], v[162:163], 0, s[46:47]
	global_load_dwordx4 v[212:215], v[164:165], off
	s_and_b64 vcc, exec, s[8:9]
	s_cbranch_vccz .Lg0_nobar
	s_barrier

; #define PG8_STAGE(bufoff, gbase, voff) do { _Pragma("unroll") for (int _i = 0; _i < 2; ++_i) \
;         __builtin_amdgcn_global_load_lds((const unsigned*)((const char*)(gbase) + (voff)[_i]), (PG8_LAS unsigned*)(lds + (bufoff) + ldsw + _i * 8192), 16, 0, 0); } while (0)
; #define PG8_LDA(dst, b, h) do { _Pragma("unroll") for (int m = 0; m < 4; ++m) _Pragma("unroll") for (int k = 0; k < 2; ++k) dst[m][k] = *(const PG8_LAS bf16x8*)(lds + PG8_SA(b, h) + aoff + m * 2048 + k * 1024); } while (0)
; #define PG8_LDB(dst, b, h) do { _Pragma("unroll") for (int n = 0; n < 2; ++n) _Pragma("unroll") for (int k = 0; k < 2; ++k) dst[n][k] = *(const PG8_LAS bf16x8*)(lds + PG8_SB(b, h) + boff + n * 2048 + k * 1024); } while (0)
; #define PG8_MMA(ai, bj, At, Bt) do { __builtin_amdgcn_s_setprio(1); _Pragma("unroll") for (int m = 0; m < 4; ++m) _Pragma("unroll") for (int n = 0; n < 2; ++n) _Pragma("unroll") for (int k = 0; k < 2; ++k) \
;         acc[ai][bj][m][n] = __builtin_amdgcn_mfma_f32_16x16x32_bf16(Bt[n][k], At[m][k], acc[ai][bj][m][n], 0, 0, 0); __builtin_amdgcn_s_setprio(0); } while (0)
; #define PG8_WAIT_V(n) asm volatile("s_waitcnt vmcnt(" #n ")" ::: "memory")
; #define PG8_WAIT_L(n) asm volatile("s_waitcnt lgkmcnt(" #n ")" ::: "memory")
; #define PG8_BAR __builtin_amdgcn_s_barrier()
; #define PG8_SCHED __builtin_amdgcn_sched_barrier(0)
; template <class Epi, class Sched, bool ALIGN_EPI = false, bool SP2 = false>
; __device__ __forceinline__ void gemm_phase(PG8_LAS unsigned char* lds, const Gemm g, const Sched& S, const Epi& E) {
;     ...
;             if constexpr (SP2) {
;             PG8_LDB(B0, 0, 0); PG8_LDB(B1, 0, 1); PG8_SCHED; PG8_LDA(At, 0, 0); PG8_STAGE(PG8_SA(1, 1), a1 + hstep, voffA);
;             PG8_WAIT_V(8); PG8_WAIT_L(0); PG8_BAR; PG8_MMA(0, 0, At, B0); PG8_MMA(0, 1, At, B1); PG8_BAR; PG8_SCHED;
;             PG8_LDA(At, 0, 1); PG8_STAGE(PG8_SB(0, 0), b2, voffB); PG8_STAGE(PG8_SB(0, 1), b2 + hstep, voffB); PG8_STAGE(PG8_SA(0, 0), a2, voffA);
;             PG8_WAIT_V(8); PG8_WAIT_L(0); PG8_BAR; PG8_MMA(1, 0, At, B0); PG8_MMA(1, 1, At, B1); PG8_BAR; PG8_SCHED;
.LBB0_160:
	s_add_u32 s42, s36, 0x100
	s_addc_u32 s43, s37, 0
	s_add_i32 s47, 0, 0x10000
	s_cmp_eq_u32 s46, 20
	s_cselect_b32 s45, s1, s43
	s_cselect_b32 s44, s0, s42
	s_cselect_b32 s19, s7, s73
	s_cselect_b32 s18, s6, s60
	s_add_i32 s76, 0, 0x14000
	v_add_u32_e32 v174, s47, v143
	v_add_u32_e32 v186, s76, v143
	ds_read_b128 v[160:163], v174
	ds_read_b128 v[164:167], v174 offset:1024
	ds_read_b128 v[170:173], v174 offset:2048
	ds_read_b128 v[174:177], v174 offset:3072
	ds_read_b128 v[178:181], v186
	ds_read_b128 v[182:185], v186 offset:1024
	ds_read_b128 v[204:207], v186 offset:2048
	ds_read_b128 v[208:211], v186 offset:3072
	v_lshl_add_u64 v[186:187], s[36:37], 0, v[156:157]
	s_add_i32 m0, s54, 0xc000
	ds_read_b128 v[212:215], v169
	ds_read_b128 v[216:219], v169 offset:1024
	ds_read_b128 v[220:223], v169 offset:2048
	ds_read_b128 v[224:227], v169 offset:3072
	ds_read_b128 v[228:231], v169 offset:4096
	ds_read_b128 v[232:235], v169 offset:5120
	ds_read_b128 v[236:239], v169 offset:6144
	ds_read_b128 v[240:243], v169 offset:7168
	global_load_lds_dwordx4 v[186:187], off
	v_lshl_add_u64 v[186:187], s[36:37], 0, v[158:159]
	s_add_i32 m0, s54, 0xe000
	s_nop 0
	global_load_lds_dwordx4 v[186:187], off
	s_waitcnt vmcnt(8)
	s_waitcnt lgkmcnt(0)
	s_barrier
	s_setprio 1
	s_waitcnt lgkmcnt(0)
	v_mfma_f32_16x16x32_bf16 v[126:129], v[160:163], v[212:215], v[126:129]
	v_mfma_f32_16x16x32_bf16 v[122:125], v[170:173], v[212:215], v[122:125]
	v_mfma_f32_16x16x32_bf16 v[110:113], v[160:163], v[220:223], v[110:113]
	v_mfma_f32_16x16x32_bf16 v[106:109], v[170:173], v[220:223], v[106:109]
	v_mfma_f32_16x16x32_bf16 v[94:97], v[160:163], v[228:231], v[94:97]
	v_mfma_f32_16x16x32_bf16 v[90:93], v[170:173], v[228:231], v[90:93]
	v_mfma_f32_16x16x32_bf16 v[78:81], v[160:163], v[236:239], v[78:81]
	v_mfma_f32_16x16x32_bf16 v[74:77], v[170:173], v[236:239], v[74:77]
	s_setprio 0
	s_setprio 1
	v_mfma_f32_16x16x32_bf16 v[126:129], v[164:167], v[216:219], v[126:129]
	v_mfma_f32_16x16x32_bf16 v[122:125], v[174:177], v[216:219], v[122:125]
	v_mfma_f32_16x16x32_bf16 v[110:113], v[164:167], v[224:227], v[110:113]
	v_mfma_f32_16x16x32_bf16 v[106:109], v[174:177], v[224:227], v[106:109]
	v_mfma_f32_16x16x32_bf16 v[94:97], v[164:167], v[232:235], v[94:97]
	v_mfma_f32_16x16x32_bf16 v[90:93], v[174:177], v[232:235], v[90:93]
	v_mfma_f32_16x16x32_bf16 v[78:81], v[164:167], v[240:243], v[78:81]
	v_mfma_f32_16x16x32_bf16 v[74:77], v[174:177], v[240:243], v[74:77]
	s_setprio 0
	s_setprio 1
	v_mfma_f32_16x16x32_bf16 v[118:121], v[178:181], v[212:215], v[118:121]
	v_mfma_f32_16x16x32_bf16 v[114:117], v[204:207], v[212:215], v[114:117]
	v_mfma_f32_16x16x32_bf16 v[102:105], v[178:181], v[220:223], v[102:105]
	v_mfma_f32_16x16x32_bf16 v[98:101], v[204:207], v[220:223], v[98:101]
	v_mfma_f32_16x16x32_bf16 v[86:89], v[178:181], v[228:231], v[86:89]
	v_mfma_f32_16x16x32_bf16 v[82:85], v[204:207], v[228:231], v[82:85]
	v_mfma_f32_16x16x32_bf16 v[70:73], v[178:181], v[236:239], v[70:73]
	v_mfma_f32_16x16x32_bf16 v[66:69], v[204:207], v[236:239], v[66:69]
	s_setprio 0
	s_setprio 1
	v_mfma_f32_16x16x32_bf16 v[118:121], v[182:185], v[216:219], v[118:121]
	v_mfma_f32_16x16x32_bf16 v[114:117], v[208:211], v[216:219], v[114:117]
	v_mfma_f32_16x16x32_bf16 v[102:105], v[182:185], v[224:227], v[102:105]
	v_mfma_f32_16x16x32_bf16 v[98:101], v[208:211], v[224:227], v[98:101]
	v_mfma_f32_16x16x32_bf16 v[86:89], v[182:185], v[232:235], v[86:89]
	v_mfma_f32_16x16x32_bf16 v[82:85], v[208:211], v[232:235], v[82:85]
	v_mfma_f32_16x16x32_bf16 v[70:73], v[182:185], v[240:243], v[70:73]
	v_mfma_f32_16x16x32_bf16 v[66:69], v[208:211], v[240:243], v[66:69]
	s_setprio 0
	s_barrier
	s_add_i32 s36, s47, s4
	v_lshl_add_u64 v[186:187], s[18:19], 0, v[148:149]
	s_mov_b32 m0, s36
	ds_read_b128 v[212:215], v169 offset:16384
	ds_read_b128 v[216:219], v169 offset:17408
	ds_read_b128 v[220:223], v169 offset:18432
	ds_read_b128 v[224:227], v169 offset:19456
	ds_read_b128 v[228:231], v169 offset:20480
	ds_read_b128 v[232:235], v169 offset:21504
	ds_read_b128 v[236:239], v169 offset:22528
	ds_read_b128 v[240:243], v169 offset:23552
	global_load_lds_dwordx4 v[186:187], off
	s_add_i32 m0, s36, 0x2000
	s_add_u32 s36, s18, 0x60000
	v_lshl_add_u64 v[244:245], s[18:19], 0, v[144:145]
	s_addc_u32 s37, s19, 0
	s_add_i32 s47, s76, s4
	global_load_lds_dwordx4 v[244:245], off
	v_lshl_add_u64 v[246:247], s[36:37], 0, v[148:149]
	s_mov_b32 m0, s47
	v_lshl_add_u64 v[248:249], s[44:45], 0, v[146:147]
	global_load_lds_dwordx4 v[246:247], off
	v_lshl_add_u64 v[246:247], s[36:37], 0, v[144:145]
	s_add_i32 m0, s47, 0x2000
	s_nop 0
	global_load_lds_dwordx4 v[246:247], off
	v_lshl_add_u64 v[246:247], s[44:45], 0, v[150:151]
	s_mov_b32 m0, s54
	s_nop 0
	global_load_lds_dwordx4 v[246:247], off
	s_mov_b32 m0, s57
	s_nop 0
	global_load_lds_dwordx4 v[248:249], off
	s_waitcnt vmcnt(8)
	s_waitcnt lgkmcnt(0)
	s_barrier
; #define PG8_STAGE(bufoff, gbase, voff) do { _Pragma("unroll") for (int _i = 0; _i < 2; ++_i) \
;         __builtin_amdgcn_global_load_lds((const unsigned*)((const char*)(gbase) + (voff)[_i]), (PG8_LAS unsigned*)(lds + (bufoff) + ldsw + _i * 8192), 16, 0, 0); } while (0)
; #define PG8_LDA(dst, b, h) do { _Pragma("unroll") for (int m = 0; m < 4; ++m) _Pragma("unroll") for (int k = 0; k < 2; ++k) dst[m][k] = *(const PG8_LAS bf16x8*)(lds + PG8_SA(b, h) + aoff + m * 2048 + k * 1024); } while (0)
; #define PG8_LDB(dst, b, h) do { _Pragma("unroll") for (int n = 0; n < 2; ++n) _Pragma("unroll") for (int k = 0; k < 2; ++k) dst[n][k] = *(const PG8_LAS bf16x8*)(lds + PG8_SB(b, h) + boff + n * 2048 + k * 1024); } while (0)
; #define PG8_MMA(ai, bj, At, Bt) do { __builtin_amdgcn_s_setprio(1); _Pragma("unroll") for (int m = 0; m < 4; ++m) _Pragma("unroll") for (int n = 0; n < 2; ++n) _Pragma("unroll") for (int k = 0; k < 2; ++k) \
;         acc[ai][bj][m][n] = __builtin_amdgcn_mfma_f32_16x16x32_bf16(Bt[n][k], At[m][k], acc[ai][bj][m][n], 0, 0, 0); __builtin_amdgcn_s_setprio(0); } while (0)
; #define PG8_WAIT_V(n) asm volatile("s_waitcnt vmcnt(" #n ")" ::: "memory")
; #define PG8_WAIT_L(n) asm volatile("s_waitcnt lgkmcnt(" #n ")" ::: "memory")
; #define PG8_BAR __builtin_amdgcn_s_barrier()
; #define PG8_SCHED __builtin_amdgcn_sched_barrier(0)
; template <class Epi, class Sched, bool ALIGN_EPI = false, bool SP2 = false>
; __device__ __forceinline__ void gemm_phase(PG8_LAS unsigned char* lds, const Gemm g, const Sched& S, const Epi& E) {
;     ...
;             PG8_WAIT_V(8); PG8_WAIT_L(0); PG8_BAR; PG8_MMA(1, 0, At, B0); PG8_MMA(1, 1, At, B1); PG8_BAR; PG8_SCHED;
;             PG8_LDB(B0, 1, 0); PG8_LDB(B1, 1, 1); PG8_SCHED; PG8_LDA(At, 1, 0); PG8_STAGE(PG8_SA(0, 1), a2 + hstep, voffA);
;             PG8_WAIT_V(8); PG8_WAIT_L(0); PG8_BAR; PG8_MMA(0, 0, At, B0); PG8_MMA(0, 1, At, B1); PG8_BAR; PG8_SCHED;
	s_setprio 1
	s_waitcnt lgkmcnt(0)
	v_mfma_f32_16x16x32_bf16 v[62:65], v[160:163], v[212:215], v[62:65]
	v_mfma_f32_16x16x32_bf16 v[58:61], v[170:173], v[212:215], v[58:61]
	v_mfma_f32_16x16x32_bf16 v[46:49], v[160:163], v[220:223], v[46:49]
	v_mfma_f32_16x16x32_bf16 v[42:45], v[170:173], v[220:223], v[42:45]
	v_mfma_f32_16x16x32_bf16 v[30:33], v[160:163], v[228:231], v[30:33]
	v_mfma_f32_16x16x32_bf16 v[26:29], v[170:173], v[228:231], v[26:29]
	v_mfma_f32_16x16x32_bf16 v[14:17], v[160:163], v[236:239], v[14:17]
	v_mfma_f32_16x16x32_bf16 v[10:13], v[170:173], v[236:239], v[10:13]
	s_setprio 0
	s_setprio 1
	v_mfma_f32_16x16x32_bf16 v[62:65], v[164:167], v[216:219], v[62:65]
	v_mfma_f32_16x16x32_bf16 v[58:61], v[174:177], v[216:219], v[58:61]
	v_mfma_f32_16x16x32_bf16 v[46:49], v[164:167], v[224:227], v[46:49]
	v_mfma_f32_16x16x32_bf16 v[42:45], v[174:177], v[224:227], v[42:45]
	v_mfma_f32_16x16x32_bf16 v[30:33], v[164:167], v[232:235], v[30:33]
	v_mfma_f32_16x16x32_bf16 v[26:29], v[174:177], v[232:235], v[26:29]
	v_mfma_f32_16x16x32_bf16 v[14:17], v[164:167], v[240:243], v[14:17]
	v_mfma_f32_16x16x32_bf16 v[10:13], v[174:177], v[240:243], v[10:13]
	s_setprio 0
	s_setprio 1
	v_mfma_f32_16x16x32_bf16 v[54:57], v[178:181], v[212:215], v[54:57]
	v_mfma_f32_16x16x32_bf16 v[50:53], v[204:207], v[212:215], v[50:53]
	v_mfma_f32_16x16x32_bf16 v[38:41], v[178:181], v[220:223], v[38:41]
	v_mfma_f32_16x16x32_bf16 v[34:37], v[204:207], v[220:223], v[34:37]
	v_mfma_f32_16x16x32_bf16 v[22:25], v[178:181], v[228:231], v[22:25]
	v_mfma_f32_16x16x32_bf16 v[18:21], v[204:207], v[228:231], v[18:21]
	v_mfma_f32_16x16x32_bf16 v[6:9], v[178:181], v[236:239], v[6:9]
	v_mfma_f32_16x16x32_bf16 v[2:5], v[204:207], v[236:239], v[2:5]
	s_setprio 0
	s_setprio 1
	v_mfma_f32_16x16x32_bf16 v[54:57], v[182:185], v[216:219], v[54:57]
	v_mfma_f32_16x16x32_bf16 v[50:53], v[208:211], v[216:219], v[50:53]
	v_mfma_f32_16x16x32_bf16 v[38:41], v[182:185], v[224:227], v[38:41]
	v_mfma_f32_16x16x32_bf16 v[34:37], v[208:211], v[224:227], v[34:37]
	v_mfma_f32_16x16x32_bf16 v[22:25], v[182:185], v[232:235], v[22:25]
	v_mfma_f32_16x16x32_bf16 v[18:21], v[208:211], v[232:235], v[18:21]
	v_mfma_f32_16x16x32_bf16 v[6:9], v[182:185], v[240:243], v[6:9]
	v_mfma_f32_16x16x32_bf16 v[2:5], v[208:211], v[240:243], v[2:5]
	s_setprio 0
	s_barrier
	s_add_i32 s47, 0, 0x18000
	s_add_i32 s76, 0, 0x1c000
	v_add_u32_e32 v174, s47, v143
	v_add_u32_e32 v203, s76, v143
	ds_read_b128 v[160:163], v174
	ds_read_b128 v[164:167], v174 offset:1024
	ds_read_b128 v[170:173], v174 offset:2048
	ds_read_b128 v[174:177], v174 offset:3072
	ds_read_b128 v[178:181], v203
	ds_read_b128 v[182:185], v203 offset:1024
	ds_read_b128 v[204:207], v203 offset:2048
	ds_read_b128 v[208:211], v203 offset:3072
	s_add_u32 s36, s44, 0x60000
	s_addc_u32 s37, s45, 0
	s_mov_b32 m0, s58
	v_lshl_add_u64 v[250:251], s[36:37], 0, v[150:151]
	ds_read_b128 v[212:215], v169 offset:32768
	ds_read_b128 v[216:219], v169 offset:33792
	ds_read_b128 v[220:223], v169 offset:34816
	ds_read_b128 v[224:227], v169 offset:35840
	ds_read_b128 v[228:231], v169 offset:36864
	ds_read_b128 v[232:235], v169 offset:37888
	ds_read_b128 v[236:239], v169 offset:38912
	ds_read_b128 v[240:243], v169 offset:39936
	global_load_lds_dwordx4 v[250:251], off
	v_lshl_add_u64 v[250:251], s[36:37], 0, v[146:147]
	s_mov_b32 m0, s59
	s_nop 0
	global_load_lds_dwordx4 v[250:251], off
	s_waitcnt vmcnt(8)
	s_waitcnt lgkmcnt(0)
	s_barrier
	s_setprio 1
	s_waitcnt lgkmcnt(0)
	v_mfma_f32_16x16x32_bf16 v[126:129], v[160:163], v[212:215], v[126:129]
	v_mfma_f32_16x16x32_bf16 v[122:125], v[170:173], v[212:215], v[122:125]
	v_mfma_f32_16x16x32_bf16 v[110:113], v[160:163], v[220:223], v[110:113]
	v_mfma_f32_16x16x32_bf16 v[106:109], v[170:173], v[220:223], v[106:109]
	v_mfma_f32_16x16x32_bf16 v[94:97], v[160:163], v[228:231], v[94:97]
	v_mfma_f32_16x16x32_bf16 v[90:93], v[170:173], v[228:231], v[90:93]
	v_mfma_f32_16x16x32_bf16 v[78:81], v[160:163], v[236:239], v[78:81]
	v_mfma_f32_16x16x32_bf16 v[74:77], v[170:173], v[236:239], v[74:77]
	s_setprio 0
	s_setprio 1
	v_mfma_f32_16x16x32_bf16 v[126:129], v[164:167], v[216:219], v[126:129]
	v_mfma_f32_16x16x32_bf16 v[122:125], v[174:177], v[216:219], v[122:125]
	v_mfma_f32_16x16x32_bf16 v[110:113], v[164:167], v[224:227], v[110:113]
	v_mfma_f32_16x16x32_bf16 v[106:109], v[174:177], v[224:227], v[106:109]
	v_mfma_f32_16x16x32_bf16 v[94:97], v[164:167], v[232:235], v[94:97]
	v_mfma_f32_16x16x32_bf16 v[90:93], v[174:177], v[232:235], v[90:93]
	v_mfma_f32_16x16x32_bf16 v[78:81], v[164:167], v[240:243], v[78:81]
	v_mfma_f32_16x16x32_bf16 v[74:77], v[174:177], v[240:243], v[74:77]
	s_setprio 0
	s_setprio 1
	v_mfma_f32_16x16x32_bf16 v[118:121], v[178:181], v[212:215], v[118:121]
	v_mfma_f32_16x16x32_bf16 v[114:117], v[204:207], v[212:215], v[114:117]
	v_mfma_f32_16x16x32_bf16 v[102:105], v[178:181], v[220:223], v[102:105]
	v_mfma_f32_16x16x32_bf16 v[98:101], v[204:207], v[220:223], v[98:101]
	v_mfma_f32_16x16x32_bf16 v[86:89], v[178:181], v[228:231], v[86:89]
	v_mfma_f32_16x16x32_bf16 v[82:85], v[204:207], v[228:231], v[82:85]
	v_mfma_f32_16x16x32_bf16 v[70:73], v[178:181], v[236:239], v[70:73]
	v_mfma_f32_16x16x32_bf16 v[66:69], v[204:207], v[236:239], v[66:69]
	s_setprio 0
	s_setprio 1
	v_mfma_f32_16x16x32_bf16 v[118:121], v[182:185], v[216:219], v[118:121]
	v_mfma_f32_16x16x32_bf16 v[114:117], v[208:211], v[216:219], v[114:117]
	v_mfma_f32_16x16x32_bf16 v[102:105], v[182:185], v[224:227], v[102:105]
	v_mfma_f32_16x16x32_bf16 v[98:101], v[208:211], v[224:227], v[98:101]
	v_mfma_f32_16x16x32_bf16 v[86:89], v[182:185], v[232:235], v[86:89]
	v_mfma_f32_16x16x32_bf16 v[82:85], v[208:211], v[232:235], v[82:85]
	v_mfma_f32_16x16x32_bf16 v[70:73], v[182:185], v[240:243], v[70:73]
	v_mfma_f32_16x16x32_bf16 v[66:69], v[208:211], v[240:243], v[66:69]
	s_setprio 0
	s_barrier
; #define PG8_STAGE(bufoff, gbase, voff) do { _Pragma("unroll") for (int _i = 0; _i < 2; ++_i) \
;         __builtin_amdgcn_global_load_lds((const unsigned*)((const char*)(gbase) + (voff)[_i]), (PG8_LAS unsigned*)(lds + (bufoff) + ldsw + _i * 8192), 16, 0, 0); } while (0)
; #define PG8_LDA(dst, b, h) do { _Pragma("unroll") for (int m = 0; m < 4; ++m) _Pragma("unroll") for (int k = 0; k < 2; ++k) dst[m][k] = *(const PG8_LAS bf16x8*)(lds + PG8_SA(b, h) + aoff + m * 2048 + k * 1024); } while (0)
; #define PG8_MMA(ai, bj, At, Bt) do { __builtin_amdgcn_s_setprio(1); _Pragma("unroll") for (int m = 0; m < 4; ++m) _Pragma("unroll") for (int n = 0; n < 2; ++n) _Pragma("unroll") for (int k = 0; k < 2; ++k) \
;         acc[ai][bj][m][n] = __builtin_amdgcn_mfma_f32_16x16x32_bf16(Bt[n][k], At[m][k], acc[ai][bj][m][n], 0, 0, 0); __builtin_amdgcn_s_setprio(0); } while (0)
; #define PG8_WAIT_V(n) asm volatile("s_waitcnt vmcnt(" #n ")" ::: "memory")
; #define PG8_WAIT_L(n) asm volatile("s_waitcnt lgkmcnt(" #n ")" ::: "memory")
; #define PG8_BAR __builtin_amdgcn_s_barrier()
; #define PG8_SCHED __builtin_amdgcn_sched_barrier(0)
; template <class Epi, class Sched, bool ALIGN_EPI = false, bool SP2 = false>
; __device__ __forceinline__ void gemm_phase(PG8_LAS unsigned char* lds, const Gemm g, const Sched& S, const Epi& E) {
;     ...
;             PG8_LDA(At, 1, 1); PG8_STAGE(PG8_SB(1, 0), b3, voffB); PG8_STAGE(PG8_SB(1, 1), b3 + hstep, voffB); PG8_STAGE(PG8_SA(1, 0), a3, voffA);
;             PG8_WAIT_V(8); PG8_WAIT_L(0); PG8_BAR; PG8_MMA(1, 0, At, B0); PG8_MMA(1, 1, At, B1); PG8_BAR; PG8_SCHED;
;     ...
;         if constexpr (ALIGN_EPI) { if (wr == 0) PG8_BAR; }
	s_add_i32 s36, s47, s4
	v_lshl_add_u64 v[186:187], v[186:187], 0, s[68:69]
	s_mov_b32 m0, s36
	ds_read_b128 v[212:215], v169 offset:49152
	ds_read_b128 v[216:219], v169 offset:50176
	ds_read_b128 v[220:223], v169 offset:51200
	ds_read_b128 v[224:227], v169 offset:52224
	ds_read_b128 v[228:231], v169 offset:53248
	ds_read_b128 v[232:235], v169 offset:54272
	ds_read_b128 v[236:239], v169 offset:55296
	ds_read_b128 v[240:243], v169 offset:56320
	global_load_lds_dwordx4 v[186:187], off
	s_add_i32 m0, s36, 0x2000
	s_add_u32 s18, s18, 0x60080
	v_lshl_add_u64 v[186:187], v[244:245], 0, s[68:69]
	s_addc_u32 s19, s19, 0
	s_add_i32 s36, s76, s4
	global_load_lds_dwordx4 v[186:187], off
	v_lshl_add_u64 v[186:187], s[18:19], 0, v[148:149]
	s_mov_b32 m0, s36
	s_nop 0
	global_load_lds_dwordx4 v[186:187], off
	v_lshl_add_u64 v[186:187], s[18:19], 0, v[144:145]
	s_add_i32 m0, s36, 0x2000
	s_nop 0
	global_load_lds_dwordx4 v[186:187], off
	v_lshl_add_u64 v[186:187], v[246:247], 0, s[68:69]
	s_mov_b32 m0, s62
	s_nop 0
	global_load_lds_dwordx4 v[186:187], off
	v_lshl_add_u64 v[186:187], v[248:249], 0, s[68:69]
	s_mov_b32 m0, s63
	s_nop 0
	global_load_lds_dwordx4 v[186:187], off
	s_waitcnt vmcnt(8)
	s_waitcnt lgkmcnt(0)
	s_barrier
	s_setprio 1
	s_waitcnt lgkmcnt(0)
	v_mfma_f32_16x16x32_bf16 v[62:65], v[160:163], v[212:215], v[62:65]
	v_mfma_f32_16x16x32_bf16 v[58:61], v[170:173], v[212:215], v[58:61]
	v_mfma_f32_16x16x32_bf16 v[46:49], v[160:163], v[220:223], v[46:49]
	v_mfma_f32_16x16x32_bf16 v[42:45], v[170:173], v[220:223], v[42:45]
	v_mfma_f32_16x16x32_bf16 v[30:33], v[160:163], v[228:231], v[30:33]
	v_mfma_f32_16x16x32_bf16 v[26:29], v[170:173], v[228:231], v[26:29]
	v_mfma_f32_16x16x32_bf16 v[14:17], v[160:163], v[236:239], v[14:17]
	v_mfma_f32_16x16x32_bf16 v[10:13], v[170:173], v[236:239], v[10:13]
	s_setprio 0
	s_setprio 1
	v_mfma_f32_16x16x32_bf16 v[62:65], v[164:167], v[216:219], v[62:65]
	v_mfma_f32_16x16x32_bf16 v[58:61], v[174:177], v[216:219], v[58:61]
	v_mfma_f32_16x16x32_bf16 v[46:49], v[164:167], v[224:227], v[46:49]
	v_mfma_f32_16x16x32_bf16 v[42:45], v[174:177], v[224:227], v[42:45]
	v_mfma_f32_16x16x32_bf16 v[30:33], v[164:167], v[232:235], v[30:33]
	v_mfma_f32_16x16x32_bf16 v[26:29], v[174:177], v[232:235], v[26:29]
	v_mfma_f32_16x16x32_bf16 v[14:17], v[164:167], v[240:243], v[14:17]
	v_mfma_f32_16x16x32_bf16 v[10:13], v[174:177], v[240:243], v[10:13]
	s_setprio 0
	s_setprio 1
	v_mfma_f32_16x16x32_bf16 v[54:57], v[178:181], v[212:215], v[54:57]
	v_mfma_f32_16x16x32_bf16 v[50:53], v[204:207], v[212:215], v[50:53]
	v_mfma_f32_16x16x32_bf16 v[38:41], v[178:181], v[220:223], v[38:41]
	v_mfma_f32_16x16x32_bf16 v[34:37], v[204:207], v[220:223], v[34:37]
	v_mfma_f32_16x16x32_bf16 v[22:25], v[178:181], v[228:231], v[22:25]
	v_mfma_f32_16x16x32_bf16 v[18:21], v[204:207], v[228:231], v[18:21]
	v_mfma_f32_16x16x32_bf16 v[6:9], v[178:181], v[236:239], v[6:9]
	v_mfma_f32_16x16x32_bf16 v[2:5], v[204:207], v[236:239], v[2:5]
	s_setprio 0
	s_setprio 1
	v_mfma_f32_16x16x32_bf16 v[54:57], v[182:185], v[216:219], v[54:57]
	v_mfma_f32_16x16x32_bf16 v[50:53], v[208:211], v[216:219], v[50:53]
	v_mfma_f32_16x16x32_bf16 v[38:41], v[182:185], v[224:227], v[38:41]
	v_mfma_f32_16x16x32_bf16 v[34:37], v[208:211], v[224:227], v[34:37]
	v_mfma_f32_16x16x32_bf16 v[22:25], v[182:185], v[232:235], v[22:25]
	v_mfma_f32_16x16x32_bf16 v[18:21], v[208:211], v[232:235], v[18:21]
	v_mfma_f32_16x16x32_bf16 v[6:9], v[182:185], v[240:243], v[6:9]
	v_mfma_f32_16x16x32_bf16 v[2:5], v[208:211], v[240:243], v[2:5]
	s_setprio 0
	s_barrier
	s_add_i32 s46, s46, 2
	s_add_u32 s60, s60, 0x100
	s_addc_u32 s73, s73, 0
	s_cmp_gt_u32 s46, 21
	s_mov_b64 s[36:37], s[42:43]
	s_cbranch_scc0 .LBB0_160
	s_and_b64 vcc, exec, s[10:11]
	s_cbranch_vccz .LBB0_163
	s_barrier

; #define PG8_STAGE(bufoff, gbase, voff) do { _Pragma("unroll") for (int _i = 0; _i < 2; ++_i) \
;         __builtin_amdgcn_global_load_lds((const unsigned*)((const char*)(gbase) + (voff)[_i]), (PG8_LAS unsigned*)(lds + (bufoff) + ldsw + _i * 8192), 16, 0, 0); } while (0)
; #define PG8_LDA(dst, b, h) do { _Pragma("unroll") for (int m = 0; m < 4; ++m) _Pragma("unroll") for (int k = 0; k < 2; ++k) dst[m][k] = *(const PG8_LAS bf16x8*)(lds + PG8_SA(b, h) + aoff + m * 2048 + k * 1024); } while (0)
; #define PG8_LDB(dst, b, h) do { _Pragma("unroll") for (int n = 0; n < 2; ++n) _Pragma("unroll") for (int k = 0; k < 2; ++k) dst[n][k] = *(const PG8_LAS bf16x8*)(lds + PG8_SB(b, h) + boff + n * 2048 + k * 1024); } while (0)
; #define PG8_WAIT_V(n) asm volatile("s_waitcnt vmcnt(" #n ")" ::: "memory")
; #define PG8_WAIT_L(n) asm volatile("s_waitcnt lgkmcnt(" #n ")" ::: "memory")
; #define PG8_BAR __builtin_amdgcn_s_barrier()
; #define PG8_SCHED __builtin_amdgcn_sched_barrier(0)
; template <class Epi, class Sched, bool ALIGN_EPI = false, bool SP2 = false>
; __device__ __forceinline__ void gemm_phase(PG8_LAS unsigned char* lds, const Gemm g, const Sched& S, const Epi& E) {
;     ...
;         const char* nA = has_next ? (const char*)g.A + (size_t)nxt.pm * tstep : cA; const char* nB = has_next ? (const char*)g.Bt + (size_t)nxt.pn * tstep : cB;
;         for (int t = 0; t < nt; t += 2) {
;             const bool last = (t == nt - 2);
;             const char* a1 = cA + (size_t)(t + 1) * kstep;
;             const char* a2 = last ? nA : cA + (size_t)(t + 2) * kstep; const char* b2 = last ? nB : cB + (size_t)(t + 2) * kstep;
;             const char* a3 = a2 + kstep; const char* b3 = b2 + kstep;
;             if (last && has_next) S.a_ready(nxt);
;             if constexpr (SP2) {
;             PG8_LDB(B0, 0, 0); PG8_LDB(B1, 0, 1); PG8_SCHED; PG8_LDA(At, 0, 0); PG8_STAGE(PG8_SA(1, 1), a1 + hstep, voffA);
;             PG8_WAIT_V(8); PG8_WAIT_L(0); PG8_BAR; PG8_MMA(0, 0, At, B0); PG8_MMA(0, 1, At, B1); PG8_BAR; PG8_SCHED;
;             PG8_LDA(At, 0, 1); PG8_STAGE(PG8_SB(0, 0), b2, voffB); PG8_STAGE(PG8_SB(0, 1), b2 + hstep, voffB); PG8_STAGE(PG8_SA(0, 0), a2, voffA);
;             PG8_WAIT_V(8); PG8_WAIT_L(0); PG8_BAR; PG8_MMA(1, 0, At, B0); PG8_MMA(1, 1, At, B1); PG8_BAR; PG8_SCHED;
.LBB0_281:
	s_add_u32 s18, s36, 0xfff80080
	s_addc_u32 s19, s37, -1
	s_add_i32 s73, 0, 0x10000
	s_cmp_eq_u32 s67, 28
	s_cselect_b32 s43, s9, s19
	s_cselect_b32 s42, s59, s18
	v_add_u32_e32 v163, s73, v160
	s_cselect_b32 s19, s7, s63
	s_cselect_b32 s18, s60, s62
	s_add_i32 s76, 0, 0x14000
	ds_read_b128 v[156:159], v163
	ds_read_b128 v[164:167], v163 offset:1024
	ds_read_b128 v[168:171], v163 offset:2048
	ds_read_b128 v[172:175], v163 offset:3072
	v_add_u32_e32 v163, s76, v160
	ds_read_b128 v[176:179], v163
	ds_read_b128 v[180:183], v163 offset:1024
	ds_read_b128 v[184:187], v163 offset:2048
	ds_read_b128 v[204:207], v163 offset:3072
	v_lshl_add_u64 v[240:241], s[36:37], 0, v[152:153]
	s_add_i32 m0, s30, 0xc000
	ds_read_b128 v[208:211], v162
	ds_read_b128 v[212:215], v162 offset:1024
	ds_read_b128 v[216:219], v162 offset:2048
	ds_read_b128 v[220:223], v162 offset:3072
	ds_read_b128 v[224:227], v162 offset:4096
	ds_read_b128 v[228:231], v162 offset:5120
	ds_read_b128 v[232:235], v162 offset:6144
	ds_read_b128 v[236:239], v162 offset:7168
	global_load_lds_dwordx4 v[240:241], off
	v_lshl_add_u64 v[240:241], s[36:37], 0, v[154:155]
	s_add_i32 m0, s30, 0xe000
	s_nop 0
	global_load_lds_dwordx4 v[240:241], off
	s_waitcnt vmcnt(8)
	s_waitcnt lgkmcnt(0)
	s_barrier
	s_setprio 1
	s_waitcnt lgkmcnt(0)
	v_mfma_f32_16x16x32_bf16 v[126:129], v[156:159], v[208:211], v[126:129]
	v_mfma_f32_16x16x32_bf16 v[122:125], v[168:171], v[208:211], v[122:125]
	v_mfma_f32_16x16x32_bf16 v[110:113], v[156:159], v[216:219], v[110:113]
	v_mfma_f32_16x16x32_bf16 v[106:109], v[168:171], v[216:219], v[106:109]
	v_mfma_f32_16x16x32_bf16 v[94:97], v[156:159], v[224:227], v[94:97]
	v_mfma_f32_16x16x32_bf16 v[90:93], v[168:171], v[224:227], v[90:93]
	v_mfma_f32_16x16x32_bf16 v[78:81], v[156:159], v[232:235], v[78:81]
	v_mfma_f32_16x16x32_bf16 v[74:77], v[168:171], v[232:235], v[74:77]
	s_setprio 0
	s_setprio 1
	v_mfma_f32_16x16x32_bf16 v[126:129], v[164:167], v[212:215], v[126:129]
	v_mfma_f32_16x16x32_bf16 v[122:125], v[172:175], v[212:215], v[122:125]
	v_mfma_f32_16x16x32_bf16 v[110:113], v[164:167], v[220:223], v[110:113]
	v_mfma_f32_16x16x32_bf16 v[106:109], v[172:175], v[220:223], v[106:109]
	v_mfma_f32_16x16x32_bf16 v[94:97], v[164:167], v[228:231], v[94:97]
	v_mfma_f32_16x16x32_bf16 v[90:93], v[172:175], v[228:231], v[90:93]
	v_mfma_f32_16x16x32_bf16 v[78:81], v[164:167], v[236:239], v[78:81]
	v_mfma_f32_16x16x32_bf16 v[74:77], v[172:175], v[236:239], v[74:77]
	s_setprio 0
	s_setprio 1
	v_mfma_f32_16x16x32_bf16 v[118:121], v[176:179], v[208:211], v[118:121]
	v_mfma_f32_16x16x32_bf16 v[114:117], v[184:187], v[208:211], v[114:117]
	v_mfma_f32_16x16x32_bf16 v[102:105], v[176:179], v[216:219], v[102:105]
	v_mfma_f32_16x16x32_bf16 v[98:101], v[184:187], v[216:219], v[98:101]
	v_mfma_f32_16x16x32_bf16 v[86:89], v[176:179], v[224:227], v[86:89]
	v_mfma_f32_16x16x32_bf16 v[82:85], v[184:187], v[224:227], v[82:85]
	v_mfma_f32_16x16x32_bf16 v[70:73], v[176:179], v[232:235], v[70:73]
	v_mfma_f32_16x16x32_bf16 v[66:69], v[184:187], v[232:235], v[66:69]
	s_setprio 0
	s_setprio 1
	v_mfma_f32_16x16x32_bf16 v[118:121], v[180:183], v[212:215], v[118:121]
	v_mfma_f32_16x16x32_bf16 v[114:117], v[204:207], v[212:215], v[114:117]
	v_mfma_f32_16x16x32_bf16 v[102:105], v[180:183], v[220:223], v[102:105]
	v_mfma_f32_16x16x32_bf16 v[98:101], v[204:207], v[220:223], v[98:101]
	v_mfma_f32_16x16x32_bf16 v[86:89], v[180:183], v[228:231], v[86:89]
	v_mfma_f32_16x16x32_bf16 v[82:85], v[204:207], v[228:231], v[82:85]
	v_mfma_f32_16x16x32_bf16 v[70:73], v[180:183], v[236:239], v[70:73]
	v_mfma_f32_16x16x32_bf16 v[66:69], v[204:207], v[236:239], v[66:69]
	s_setprio 0
	s_barrier
	s_add_i32 s73, s73, s28
	v_lshl_add_u64 v[240:241], s[18:19], 0, v[146:147]
	s_mov_b32 m0, s73
	ds_read_b128 v[208:211], v162 offset:16384
	ds_read_b128 v[212:215], v162 offset:17408
	ds_read_b128 v[216:219], v162 offset:18432
	ds_read_b128 v[220:223], v162 offset:19456
	ds_read_b128 v[224:227], v162 offset:20480
	ds_read_b128 v[228:231], v162 offset:21504
	ds_read_b128 v[232:235], v162 offset:22528
	ds_read_b128 v[236:239], v162 offset:23552
	global_load_lds_dwordx4 v[240:241], off
	s_add_i32 m0, s73, 0x2000
	s_add_u32 s78, s18, 0x80000
	v_lshl_add_u64 v[242:243], s[18:19], 0, v[142:143]
	s_addc_u32 s79, s19, 0
	s_add_i32 s73, s76, s28
	global_load_lds_dwordx4 v[242:243], off
	v_lshl_add_u64 v[244:245], s[78:79], 0, v[146:147]
	s_mov_b32 m0, s73
	v_lshl_add_u64 v[246:247], s[42:43], 0, v[144:145]
	global_load_lds_dwordx4 v[244:245], off
	v_lshl_add_u64 v[244:245], s[78:79], 0, v[142:143]
	s_add_i32 m0, s73, 0x2000
	s_nop 0
	global_load_lds_dwordx4 v[244:245], off
	v_lshl_add_u64 v[244:245], s[42:43], 0, v[148:149]
	s_mov_b32 m0, s30
	s_nop 0
	global_load_lds_dwordx4 v[244:245], off
	s_mov_b32 m0, s34
	s_nop 0
	global_load_lds_dwordx4 v[246:247], off
	s_waitcnt vmcnt(8)
	s_waitcnt lgkmcnt(0)
	s_barrier
; #define PG8_STAGE(bufoff, gbase, voff) do { _Pragma("unroll") for (int _i = 0; _i < 2; ++_i) \
;         __builtin_amdgcn_global_load_lds((const unsigned*)((const char*)(gbase) + (voff)[_i]), (PG8_LAS unsigned*)(lds + (bufoff) + ldsw + _i * 8192), 16, 0, 0); } while (0)
; #define PG8_LDA(dst, b, h) do { _Pragma("unroll") for (int m = 0; m < 4; ++m) _Pragma("unroll") for (int k = 0; k < 2; ++k) dst[m][k] = *(const PG8_LAS bf16x8*)(lds + PG8_SA(b, h) + aoff + m * 2048 + k * 1024); } while (0)
; #define PG8_LDB(dst, b, h) do { _Pragma("unroll") for (int n = 0; n < 2; ++n) _Pragma("unroll") for (int k = 0; k < 2; ++k) dst[n][k] = *(const PG8_LAS bf16x8*)(lds + PG8_SB(b, h) + boff + n * 2048 + k * 1024); } while (0)
; #define PG8_MMA(ai, bj, At, Bt) do { __builtin_amdgcn_s_setprio(1); _Pragma("unroll") for (int m = 0; m < 4; ++m) _Pragma("unroll") for (int n = 0; n < 2; ++n) _Pragma("unroll") for (int k = 0; k < 2; ++k) \
;         acc[ai][bj][m][n] = __builtin_amdgcn_mfma_f32_16x16x32_bf16(Bt[n][k], At[m][k], acc[ai][bj][m][n], 0, 0, 0); __builtin_amdgcn_s_setprio(0); } while (0)
; #define PG8_WAIT_V(n) asm volatile("s_waitcnt vmcnt(" #n ")" ::: "memory")
; #define PG8_WAIT_L(n) asm volatile("s_waitcnt lgkmcnt(" #n ")" ::: "memory")
; #define PG8_BAR __builtin_amdgcn_s_barrier()
; #define PG8_SCHED __builtin_amdgcn_sched_barrier(0)
; template <class Epi, class Sched, bool ALIGN_EPI = false, bool SP2 = false>
; __device__ __forceinline__ void gemm_phase(PG8_LAS unsigned char* lds, const Gemm g, const Sched& S, const Epi& E) {
;     ...
;             PG8_WAIT_V(8); PG8_WAIT_L(0); PG8_BAR; PG8_MMA(1, 0, At, B0); PG8_MMA(1, 1, At, B1); PG8_BAR; PG8_SCHED;
;             PG8_LDB(B0, 1, 0); PG8_LDB(B1, 1, 1); PG8_SCHED; PG8_LDA(At, 1, 0); PG8_STAGE(PG8_SA(0, 1), a2 + hstep, voffA);
;             PG8_WAIT_V(8); PG8_WAIT_L(0); PG8_BAR; PG8_MMA(0, 0, At, B0); PG8_MMA(0, 1, At, B1); PG8_BAR; PG8_SCHED;
	s_setprio 1
	s_waitcnt lgkmcnt(0)
	v_mfma_f32_16x16x32_bf16 v[62:65], v[156:159], v[208:211], v[62:65]
	v_mfma_f32_16x16x32_bf16 v[58:61], v[168:171], v[208:211], v[58:61]
	v_mfma_f32_16x16x32_bf16 v[46:49], v[156:159], v[216:219], v[46:49]
	v_mfma_f32_16x16x32_bf16 v[42:45], v[168:171], v[216:219], v[42:45]
	v_mfma_f32_16x16x32_bf16 v[30:33], v[156:159], v[224:227], v[30:33]
	v_mfma_f32_16x16x32_bf16 v[26:29], v[168:171], v[224:227], v[26:29]
	v_mfma_f32_16x16x32_bf16 v[14:17], v[156:159], v[232:235], v[14:17]
	v_mfma_f32_16x16x32_bf16 v[10:13], v[168:171], v[232:235], v[10:13]
	s_setprio 0
	s_setprio 1
	v_mfma_f32_16x16x32_bf16 v[62:65], v[164:167], v[212:215], v[62:65]
	v_mfma_f32_16x16x32_bf16 v[58:61], v[172:175], v[212:215], v[58:61]
	v_mfma_f32_16x16x32_bf16 v[46:49], v[164:167], v[220:223], v[46:49]
	v_mfma_f32_16x16x32_bf16 v[42:45], v[172:175], v[220:223], v[42:45]
	v_mfma_f32_16x16x32_bf16 v[30:33], v[164:167], v[228:231], v[30:33]
	v_mfma_f32_16x16x32_bf16 v[26:29], v[172:175], v[228:231], v[26:29]
	v_mfma_f32_16x16x32_bf16 v[14:17], v[164:167], v[236:239], v[14:17]
	v_mfma_f32_16x16x32_bf16 v[10:13], v[172:175], v[236:239], v[10:13]
	s_setprio 0
	s_setprio 1
	v_mfma_f32_16x16x32_bf16 v[54:57], v[176:179], v[208:211], v[54:57]
	v_mfma_f32_16x16x32_bf16 v[50:53], v[184:187], v[208:211], v[50:53]
	v_mfma_f32_16x16x32_bf16 v[38:41], v[176:179], v[216:219], v[38:41]
	v_mfma_f32_16x16x32_bf16 v[34:37], v[184:187], v[216:219], v[34:37]
	v_mfma_f32_16x16x32_bf16 v[22:25], v[176:179], v[224:227], v[22:25]
	v_mfma_f32_16x16x32_bf16 v[18:21], v[184:187], v[224:227], v[18:21]
	v_mfma_f32_16x16x32_bf16 v[6:9], v[176:179], v[232:235], v[6:9]
	v_mfma_f32_16x16x32_bf16 v[2:5], v[184:187], v[232:235], v[2:5]
	s_setprio 0
	s_setprio 1
	v_mfma_f32_16x16x32_bf16 v[54:57], v[180:183], v[212:215], v[54:57]
	v_mfma_f32_16x16x32_bf16 v[50:53], v[204:207], v[212:215], v[50:53]
	v_mfma_f32_16x16x32_bf16 v[38:41], v[180:183], v[220:223], v[38:41]
	v_mfma_f32_16x16x32_bf16 v[34:37], v[204:207], v[220:223], v[34:37]
	v_mfma_f32_16x16x32_bf16 v[22:25], v[180:183], v[228:231], v[22:25]
	v_mfma_f32_16x16x32_bf16 v[18:21], v[204:207], v[228:231], v[18:21]
	v_mfma_f32_16x16x32_bf16 v[6:9], v[180:183], v[236:239], v[6:9]
	v_mfma_f32_16x16x32_bf16 v[2:5], v[204:207], v[236:239], v[2:5]
	s_setprio 0
	s_barrier
	s_add_i32 s73, 0, 0x18000
	v_add_u32_e32 v163, s73, v160
	s_add_i32 s76, 0, 0x1c000
	ds_read_b128 v[156:159], v163
	ds_read_b128 v[164:167], v163 offset:1024
	ds_read_b128 v[168:171], v163 offset:2048
	ds_read_b128 v[172:175], v163 offset:3072
	v_add_u32_e32 v163, s76, v160
	ds_read_b128 v[176:179], v163
	ds_read_b128 v[180:183], v163 offset:1024
	ds_read_b128 v[184:187], v163 offset:2048
	ds_read_b128 v[204:207], v163 offset:3072
	s_add_u32 s42, s42, 0x80000
	s_addc_u32 s43, s43, 0
	s_mov_b32 m0, s44
	v_lshl_add_u64 v[248:249], s[42:43], 0, v[148:149]
	ds_read_b128 v[208:211], v162 offset:32768
	ds_read_b128 v[212:215], v162 offset:33792
	ds_read_b128 v[216:219], v162 offset:34816
	ds_read_b128 v[220:223], v162 offset:35840
	ds_read_b128 v[224:227], v162 offset:36864
	ds_read_b128 v[228:231], v162 offset:37888
	ds_read_b128 v[232:235], v162 offset:38912
	ds_read_b128 v[236:239], v162 offset:39936
	global_load_lds_dwordx4 v[248:249], off
	v_lshl_add_u64 v[248:249], s[42:43], 0, v[144:145]
	s_mov_b32 m0, s45
	s_nop 0
	global_load_lds_dwordx4 v[248:249], off
	s_waitcnt vmcnt(8)
	s_waitcnt lgkmcnt(0)
	s_barrier
	s_setprio 1
	s_waitcnt lgkmcnt(0)
	v_mfma_f32_16x16x32_bf16 v[126:129], v[156:159], v[208:211], v[126:129]
	v_mfma_f32_16x16x32_bf16 v[122:125], v[168:171], v[208:211], v[122:125]
	v_mfma_f32_16x16x32_bf16 v[110:113], v[156:159], v[216:219], v[110:113]
	v_mfma_f32_16x16x32_bf16 v[106:109], v[168:171], v[216:219], v[106:109]
	v_mfma_f32_16x16x32_bf16 v[94:97], v[156:159], v[224:227], v[94:97]
	v_mfma_f32_16x16x32_bf16 v[90:93], v[168:171], v[224:227], v[90:93]
	v_mfma_f32_16x16x32_bf16 v[78:81], v[156:159], v[232:235], v[78:81]
	v_mfma_f32_16x16x32_bf16 v[74:77], v[168:171], v[232:235], v[74:77]
	s_setprio 0
	s_setprio 1
	v_mfma_f32_16x16x32_bf16 v[126:129], v[164:167], v[212:215], v[126:129]
	v_mfma_f32_16x16x32_bf16 v[122:125], v[172:175], v[212:215], v[122:125]
	v_mfma_f32_16x16x32_bf16 v[110:113], v[164:167], v[220:223], v[110:113]
	v_mfma_f32_16x16x32_bf16 v[106:109], v[172:175], v[220:223], v[106:109]
	v_mfma_f32_16x16x32_bf16 v[94:97], v[164:167], v[228:231], v[94:97]
	v_mfma_f32_16x16x32_bf16 v[90:93], v[172:175], v[228:231], v[90:93]
	v_mfma_f32_16x16x32_bf16 v[78:81], v[164:167], v[236:239], v[78:81]
	v_mfma_f32_16x16x32_bf16 v[74:77], v[172:175], v[236:239], v[74:77]
	s_setprio 0
	s_setprio 1
	v_mfma_f32_16x16x32_bf16 v[118:121], v[176:179], v[208:211], v[118:121]
	v_mfma_f32_16x16x32_bf16 v[114:117], v[184:187], v[208:211], v[114:117]
	v_mfma_f32_16x16x32_bf16 v[102:105], v[176:179], v[216:219], v[102:105]
	v_mfma_f32_16x16x32_bf16 v[98:101], v[184:187], v[216:219], v[98:101]
	v_mfma_f32_16x16x32_bf16 v[86:89], v[176:179], v[224:227], v[86:89]
	v_mfma_f32_16x16x32_bf16 v[82:85], v[184:187], v[224:227], v[82:85]
	v_mfma_f32_16x16x32_bf16 v[70:73], v[176:179], v[232:235], v[70:73]
	v_mfma_f32_16x16x32_bf16 v[66:69], v[184:187], v[232:235], v[66:69]
	s_setprio 0
	s_setprio 1
	v_mfma_f32_16x16x32_bf16 v[118:121], v[180:183], v[212:215], v[118:121]
	v_mfma_f32_16x16x32_bf16 v[114:117], v[204:207], v[212:215], v[114:117]
	v_mfma_f32_16x16x32_bf16 v[102:105], v[180:183], v[220:223], v[102:105]
	v_mfma_f32_16x16x32_bf16 v[98:101], v[204:207], v[220:223], v[98:101]
	v_mfma_f32_16x16x32_bf16 v[86:89], v[180:183], v[228:231], v[86:89]
	v_mfma_f32_16x16x32_bf16 v[82:85], v[204:207], v[228:231], v[82:85]
	v_mfma_f32_16x16x32_bf16 v[70:73], v[180:183], v[236:239], v[70:73]
	v_mfma_f32_16x16x32_bf16 v[66:69], v[204:207], v[236:239], v[66:69]
	s_setprio 0
	s_barrier
; #define PG8_STAGE(bufoff, gbase, voff) do { _Pragma("unroll") for (int _i = 0; _i < 2; ++_i) \
;         __builtin_amdgcn_global_load_lds((const unsigned*)((const char*)(gbase) + (voff)[_i]), (PG8_LAS unsigned*)(lds + (bufoff) + ldsw + _i * 8192), 16, 0, 0); } while (0)
; #define PG8_LDA(dst, b, h) do { _Pragma("unroll") for (int m = 0; m < 4; ++m) _Pragma("unroll") for (int k = 0; k < 2; ++k) dst[m][k] = *(const PG8_LAS bf16x8*)(lds + PG8_SA(b, h) + aoff + m * 2048 + k * 1024); } while (0)
; #define PG8_MMA(ai, bj, At, Bt) do { __builtin_amdgcn_s_setprio(1); _Pragma("unroll") for (int m = 0; m < 4; ++m) _Pragma("unroll") for (int n = 0; n < 2; ++n) _Pragma("unroll") for (int k = 0; k < 2; ++k) \
;         acc[ai][bj][m][n] = __builtin_amdgcn_mfma_f32_16x16x32_bf16(Bt[n][k], At[m][k], acc[ai][bj][m][n], 0, 0, 0); __builtin_amdgcn_s_setprio(0); } while (0)
; #define PG8_WAIT_V(n) asm volatile("s_waitcnt vmcnt(" #n ")" ::: "memory")
; #define PG8_WAIT_L(n) asm volatile("s_waitcnt lgkmcnt(" #n ")" ::: "memory")
; #define PG8_BAR __builtin_amdgcn_s_barrier()
; #define PG8_SCHED __builtin_amdgcn_sched_barrier(0)
;     __device__ __forceinline__ void operator()(const f32x4 (&acc)[2][2][4][2], const Unit& u, int wr, int wc, int fr, int fq) const {
;     ...
;         if (u.pn >= 30) {
; template <class Epi, class Sched, bool ALIGN_EPI = false, bool SP2 = false>
; __device__ __forceinline__ void gemm_phase(PG8_LAS unsigned char* lds, const Gemm g, const Sched& S, const Epi& E) {
;     ...
;             PG8_LDA(At, 1, 1); PG8_STAGE(PG8_SB(1, 0), b3, voffB); PG8_STAGE(PG8_SB(1, 1), b3 + hstep, voffB); PG8_STAGE(PG8_SA(1, 0), a3, voffA);
;             PG8_WAIT_V(8); PG8_WAIT_L(0); PG8_BAR; PG8_MMA(1, 0, At, B0); PG8_MMA(1, 1, At, B1); PG8_BAR; PG8_SCHED;
	s_add_i32 s42, s73, s28
	v_lshl_add_u64 v[240:241], v[240:241], 0, s[68:69]
	s_mov_b32 m0, s42
	ds_read_b128 v[208:211], v162 offset:49152
	ds_read_b128 v[212:215], v162 offset:50176
	ds_read_b128 v[216:219], v162 offset:51200
	ds_read_b128 v[220:223], v162 offset:52224
	ds_read_b128 v[224:227], v162 offset:53248
	ds_read_b128 v[228:231], v162 offset:54272
	ds_read_b128 v[232:235], v162 offset:55296
	ds_read_b128 v[236:239], v162 offset:56320
	global_load_lds_dwordx4 v[240:241], off
	s_add_i32 m0, s42, 0x2000
	s_add_u32 s18, s18, 0x80080
	v_lshl_add_u64 v[240:241], v[242:243], 0, s[68:69]
	s_addc_u32 s19, s19, 0
	s_add_i32 s42, s76, s28
	global_load_lds_dwordx4 v[240:241], off
	v_lshl_add_u64 v[240:241], s[18:19], 0, v[146:147]
	s_mov_b32 m0, s42
	s_nop 0
	global_load_lds_dwordx4 v[240:241], off
	v_lshl_add_u64 v[240:241], s[18:19], 0, v[142:143]
	s_add_i32 m0, s42, 0x2000
	s_nop 0
	global_load_lds_dwordx4 v[240:241], off
	v_lshl_add_u64 v[240:241], v[244:245], 0, s[68:69]
	s_mov_b32 m0, s46
	s_nop 0
	global_load_lds_dwordx4 v[240:241], off
	v_lshl_add_u64 v[240:241], v[246:247], 0, s[68:69]
	s_mov_b32 m0, s47
	s_nop 0
	global_load_lds_dwordx4 v[240:241], off
	s_waitcnt vmcnt(8)
	s_waitcnt lgkmcnt(0)
	s_barrier
	s_setprio 1
	s_waitcnt lgkmcnt(0)
	v_mfma_f32_16x16x32_bf16 v[62:65], v[156:159], v[208:211], v[62:65]
	v_mfma_f32_16x16x32_bf16 v[58:61], v[168:171], v[208:211], v[58:61]
	v_mfma_f32_16x16x32_bf16 v[46:49], v[156:159], v[216:219], v[46:49]
	v_mfma_f32_16x16x32_bf16 v[42:45], v[168:171], v[216:219], v[42:45]
	v_mfma_f32_16x16x32_bf16 v[30:33], v[156:159], v[224:227], v[30:33]
	v_mfma_f32_16x16x32_bf16 v[26:29], v[168:171], v[224:227], v[26:29]
	v_mfma_f32_16x16x32_bf16 v[14:17], v[156:159], v[232:235], v[14:17]
	v_mfma_f32_16x16x32_bf16 v[10:13], v[168:171], v[232:235], v[10:13]
	s_setprio 0
	s_setprio 1
	v_mfma_f32_16x16x32_bf16 v[62:65], v[164:167], v[212:215], v[62:65]
	v_mfma_f32_16x16x32_bf16 v[58:61], v[172:175], v[212:215], v[58:61]
	v_mfma_f32_16x16x32_bf16 v[46:49], v[164:167], v[220:223], v[46:49]
	v_mfma_f32_16x16x32_bf16 v[42:45], v[172:175], v[220:223], v[42:45]
	v_mfma_f32_16x16x32_bf16 v[30:33], v[164:167], v[228:231], v[30:33]
	v_mfma_f32_16x16x32_bf16 v[26:29], v[172:175], v[228:231], v[26:29]
	v_mfma_f32_16x16x32_bf16 v[14:17], v[164:167], v[236:239], v[14:17]
	v_mfma_f32_16x16x32_bf16 v[10:13], v[172:175], v[236:239], v[10:13]
	s_setprio 0
	s_setprio 1
	v_mfma_f32_16x16x32_bf16 v[54:57], v[176:179], v[208:211], v[54:57]
	v_mfma_f32_16x16x32_bf16 v[50:53], v[184:187], v[208:211], v[50:53]
	v_mfma_f32_16x16x32_bf16 v[38:41], v[176:179], v[216:219], v[38:41]
	v_mfma_f32_16x16x32_bf16 v[34:37], v[184:187], v[216:219], v[34:37]
	v_mfma_f32_16x16x32_bf16 v[22:25], v[176:179], v[224:227], v[22:25]
	v_mfma_f32_16x16x32_bf16 v[18:21], v[184:187], v[224:227], v[18:21]
	v_mfma_f32_16x16x32_bf16 v[6:9], v[176:179], v[232:235], v[6:9]
	v_mfma_f32_16x16x32_bf16 v[2:5], v[184:187], v[232:235], v[2:5]
	s_setprio 0
	s_setprio 1
	v_mfma_f32_16x16x32_bf16 v[54:57], v[180:183], v[212:215], v[54:57]
	v_mfma_f32_16x16x32_bf16 v[50:53], v[204:207], v[212:215], v[50:53]
	v_mfma_f32_16x16x32_bf16 v[38:41], v[180:183], v[220:223], v[38:41]
	v_mfma_f32_16x16x32_bf16 v[34:37], v[204:207], v[220:223], v[34:37]
	v_mfma_f32_16x16x32_bf16 v[22:25], v[180:183], v[228:231], v[22:25]
	v_mfma_f32_16x16x32_bf16 v[18:21], v[204:207], v[228:231], v[18:21]
	v_mfma_f32_16x16x32_bf16 v[6:9], v[180:183], v[236:239], v[6:9]
	v_mfma_f32_16x16x32_bf16 v[2:5], v[204:207], v[236:239], v[2:5]
	s_setprio 0
	s_barrier
	s_add_i32 s67, s67, 2
	s_add_u32 s36, s36, 0x100
	s_addc_u32 s37, s37, 0
	s_add_u32 s62, s62, 0x100
	s_addc_u32 s63, s63, 0
	s_cmp_gt_u32 s67, 29
	s_cbranch_scc0 .LBB0_281
	s_and_b64 vcc, exec, s[4:5]
	s_cbranch_vccnz .LBB0_286
	s_cmp_lt_i32 s57, 30
	s_mov_b64 s[18:19], -1
	s_cbranch_scc1 .LBB0_287
